# pre phase: log1pf double-float expansion -> f32 hardware log of (1+e)
# speedup vs baseline: 1.0491x; 1.0048x over previous
.LBB0_276:
	s_lshl_b32 s10, s17, 5
	s_lshl_b32 s4, s17, 12
	s_add_i32 s20, s10, 0xfe00
	s_and_b64 s[10:11], s[12:13], exec
	s_cselect_b32 s54, s4, s20
	s_lshl_b32 s4, s19, 6
	s_waitcnt vmcnt(5)
	v_or_b32_e32 v0, s4, v154
	v_readlane_b32 s36, v253, 26
	v_lshlrev_b32_e32 v48, 2, v0
	v_readlane_b32 s38, v253, 28
	v_readlane_b32 s39, v253, 29
	s_and_b64 s[10:11], s[12:13], exec
	v_readlane_b32 s50, v253, 40
	v_lshl_add_u64 v[0:1], s[38:39], 0, v[48:49]
	v_add_co_u32_e32 v2, vcc, 0x1000, v0
	v_readlane_b32 s51, v253, 41
	s_nop 0
	v_addc_co_u32_e32 v3, vcc, 0, v1, vcc
	s_cselect_b32 s10, 0x1000, 32
	v_lshl_add_u32 v187, s18, 6, v150
	s_waitcnt vmcnt(1)
	v_add_co_u32_e32 v4, vcc, 0x2000, v0
	v_cmp_gt_u32_e64 s[50:51], s10, v187
	s_waitcnt vmcnt(0)
	v_addc_co_u32_e32 v5, vcc, 0, v1, vcc
	global_load_dword v66, v[2:3], off offset:2048
	global_load_dword v67, v[2:3], off offset:3072
	global_load_dword v68, v[4:5], off
	global_load_dword v69, v[4:5], off offset:1024
	global_load_dword v64, v[4:5], off offset:2048
	global_load_dword v65, v[4:5], off offset:3072
	v_cndmask_b32_e64 v4, 0, v187, s[50:51]
	v_add_u32_e32 v32, s54, v4
	v_ashrrev_i32_e32 v33, 31, v32
	v_lshlrev_b64 v[4:5], 6, v[32:33]
	v_add_co_u32_e32 v0, vcc, 0x3000, v0
	v_lshl_add_u64 v[34:35], s[6:7], 0, v[4:5]
	v_readlane_b32 s40, v253, 30
	v_readlane_b32 s41, v253, 31
	v_addc_co_u32_e32 v1, vcc, 0, v1, vcc
	global_load_dwordx4 v[8:11], v[34:35], off offset:16
	global_load_dwordx4 v[12:15], v[34:35], off
	global_load_dwordx4 v[36:39], v[34:35], off offset:48
	global_load_dwordx4 v[40:43], v[34:35], off offset:32
	global_load_dword v139, v48, s[38:39]
	global_load_dword v138, v48, s[40:41]
	global_load_dword v72, v[0:1], off
	global_load_dword v73, v[0:1], off offset:1024
	global_load_dword v70, v[0:1], off offset:2048
	global_load_dword v140, v48, s[38:39] offset:1024
	global_load_dword v71, v[0:1], off offset:3072
	global_load_dword v141, v48, s[38:39] offset:2048
	global_load_dword v143, v48, s[38:39] offset:3072
	global_load_dword v142, v[2:3], off
	s_nop 0
	global_load_dword v48, v[2:3], off offset:1024
	v_readlane_b32 s48, v253, 38
	v_readlane_b32 s49, v253, 39
	v_or_b32_e32 v186, 1, v187
	v_readlane_b32 s44, v253, 34
	v_readlane_b32 s45, v253, 35
	v_or_b32_e32 v184, 2, v187
	v_or_b32_e32 v182, 3, v187
	v_cmp_gt_u32_e64 s[48:49], s10, v186
	v_cmp_gt_u32_e64 s[44:45], s10, v184
	v_cmp_gt_u32_e64 s[40:41], s10, v182
	v_cndmask_b32_e64 v0, 0, v186, s[48:49]
	v_cndmask_b32_e64 v1, 0, v184, s[44:45]
	v_cndmask_b32_e64 v2, 0, v182, s[40:41]
	v_add_u32_e32 v136, s54, v0
	v_add_u32_e32 v132, s54, v1
	v_add_u32_e32 v128, s54, v2
	v_ashrrev_i32_e32 v137, 31, v136
	v_ashrrev_i32_e32 v133, 31, v132
	v_ashrrev_i32_e32 v129, 31, v128
	v_lshlrev_b64 v[0:1], 6, v[136:137]
	v_lshlrev_b64 v[2:3], 6, v[132:133]
	v_lshlrev_b64 v[4:5], 6, v[128:129]
	v_lshl_add_u64 v[44:45], s[6:7], 0, v[0:1]
	v_lshl_add_u64 v[134:135], s[6:7], 0, v[2:3]
	v_lshl_add_u64 v[130:131], s[6:7], 0, v[4:5]
	global_load_dwordx4 v[74:77], v[44:45], off offset:16
	global_load_dwordx4 v[78:81], v[44:45], off
	global_load_dwordx4 v[82:85], v[44:45], off offset:48
	global_load_dwordx4 v[86:89], v[44:45], off offset:32
	global_load_dwordx4 v[24:27], v[134:135], off offset:16
	global_load_dwordx4 v[28:31], v[134:135], off
	global_load_dwordx4 v[16:19], v[134:135], off offset:48
	global_load_dwordx4 v[20:23], v[134:135], off offset:32
	global_load_dwordx4 v[0:3], v[130:131], off offset:16
	global_load_dwordx4 v[4:7], v[130:131], off
	s_mov_b32 s11, 0x3d800000
	v_readlane_b32 s37, v253, 27
	v_readlane_b32 s42, v253, 32
	v_readlane_b32 s43, v253, 33
	v_readlane_b32 s46, v253, 36
	v_readlane_b32 s47, v253, 37
	s_waitcnt vmcnt(24)
	v_pk_mul_f32 v[10:11], v[66:67], v[10:11]
	s_waitcnt vmcnt(21)
	v_pk_mul_f32 v[40:41], v[68:69], v[40:41]
	v_pk_mul_f32 v[42:43], v[64:65], v[42:43]
	s_waitcnt vmcnt(19)
	v_fma_f32 v12, v139, v12, v138
	s_waitcnt vmcnt(17)
	v_pk_mul_f32 v[36:37], v[72:73], v[36:37]
	s_waitcnt vmcnt(15)
	v_fmac_f32_e32 v12, v140, v13
	s_waitcnt vmcnt(14)
	v_pk_mul_f32 v[38:39], v[70:71], v[38:39]
	s_waitcnt vmcnt(13)
	v_fmac_f32_e32 v12, v141, v14
	s_waitcnt vmcnt(12)
	v_fmac_f32_e32 v12, v143, v15
	s_waitcnt vmcnt(11)
	v_fmac_f32_e32 v12, v142, v8
	s_waitcnt vmcnt(10)
	v_fmac_f32_e32 v12, v48, v9
	v_add_f32_e32 v8, v12, v10
	v_add_f32_e32 v8, v8, v11
	v_add_f32_e32 v8, v8, v40
	v_add_f32_e32 v8, v8, v41
	v_add_f32_e32 v8, v8, v42
	v_add_f32_e32 v8, v8, v43
	v_add_f32_e32 v8, v8, v36
	v_add_f32_e32 v8, v8, v37
	v_add_f32_e32 v8, v8, v38
	v_add_f32_e32 v36, v8, v39
	v_mul_f32_e64 v8, |v36|, s97
	v_exp_f32_e32 v38, v8
	v_min_f32_e32 v39, 0, v36
	global_load_dwordx4 v[8:11], v[130:131], off offset:48
	global_load_dwordx4 v[12:15], v[130:131], off offset:32
	s_nop 1
	s_waitcnt vmcnt(6)
	v_fma_f32 v28, v139, v28, v138
	v_fmac_f32_e32 v28, v140, v29
	s_nop 1
	v_fmac_f32_e32 v28, v141, v30
	v_fmac_f32_e32 v28, v143, v31
	s_nop 1
	v_fmac_f32_e32 v28, v142, v24
	v_fmac_f32_e32 v28, v48, v25
	s_nop 1
	v_pk_mul_f32 v[24:25], v[66:67], v[26:27]
	s_waitcnt vmcnt(4)
	v_pk_mul_f32 v[20:21], v[68:69], v[20:21]
	s_nop 1
	v_add_f32_e32 v24, v28, v24
	v_add_f32_e32 v24, v24, v25
	v_add_f32_e32 v36, 1.0, v38
	v_log_f32_e32 v36, v36
	s_nop 0
	v_mul_f32_e32 v36, 0x3f317218, v36
	s_nop 1
	v_sub_f32_e32 v38, v39, v36
	v_fma_f32 v39, v139, v78, v138
	v_fmac_f32_e32 v39, v140, v79
	v_fmac_f32_e32 v39, v141, v80
	v_fmac_f32_e32 v39, v143, v81
	v_fmac_f32_e32 v39, v142, v74
	v_fmac_f32_e32 v39, v48, v75
	v_pk_mul_f32 v[36:37], v[66:67], v[76:77]
	v_add_f32_e32 v20, v24, v20
	v_add_f32_e32 v36, v39, v36
	v_add_f32_e32 v39, v36, v37
	v_pk_mul_f32 v[36:37], v[68:69], v[86:87]
	v_add_f32_e32 v24, v20, v21
	v_add_f32_e32 v36, v39, v36
	v_add_f32_e32 v39, v36, v37
	v_pk_mul_f32 v[36:37], v[64:65], v[88:89]
	v_pk_mul_f32 v[20:21], v[64:65], v[22:23]
	v_add_f32_e32 v36, v39, v36
	v_add_f32_e32 v39, v36, v37
	v_pk_mul_f32 v[36:37], v[72:73], v[82:83]
	v_add_f32_e32 v20, v24, v20
	v_add_f32_e32 v36, v39, v36
	v_add_f32_e32 v39, v36, v37
	v_pk_mul_f32 v[36:37], v[70:71], v[84:85]
	v_add_f32_e32 v20, v20, v21
	v_add_f32_e32 v36, v39, v36
	v_add_f32_e32 v36, v36, v37
	v_mul_f32_e64 v37, |v36|, s97
	v_exp_f32_e32 v39, v37
	v_fma_f32 v37, v38, s11, 0
	v_min_f32_e32 v40, 0, v36
	v_cndmask_b32_e64 v38, 0, v37, s[50:51]
	s_nop 1
	v_pk_mul_f32 v[16:17], v[72:73], v[16:17]
	s_waitcnt vmcnt(2)
	v_fma_f32 v4, v139, v4, v138
	s_nop 1
	v_add_f32_e32 v16, v20, v16
	s_nop 1
	v_add_f32_e32 v20, v16, v17
	v_pk_mul_f32 v[16:17], v[70:71], v[18:19]
	s_nop 1
	v_add_f32_e32 v16, v20, v16
	s_nop 1
	v_add_f32_e32 v16, v16, v17
	v_mul_f32_e64 v17, |v16|, s97
	s_nop 1
	v_exp_f32_e32 v18, v17
	v_min_f32_e32 v20, 0, v16
	s_nop 1
	v_fmac_f32_e32 v4, v140, v5
	v_add_f32_e32 v36, 1.0, v39
	v_log_f32_e32 v36, v36
	s_nop 0
	v_mul_f32_e32 v36, 0x3f317218, v36
	s_nop 1
	v_sub_f32_e32 v36, v40, v36
	v_mul_f32_e32 v36, 0x3d800000, v36
	v_cndmask_b32_e64 v17, 0, v36, s[48:49]
	v_add_f32_e32 v19, v38, v17
	s_nop 1
	v_fmac_f32_e32 v4, v141, v6
	v_fmac_f32_e32 v4, v143, v7
	s_nop 1
	v_fmac_f32_e32 v4, v142, v0
	s_nop 1
	v_fmac_f32_e32 v4, v48, v1
	v_pk_mul_f32 v[0:1], v[66:67], v[2:3]
	s_nop 1
	v_add_f32_e32 v0, v4, v0
	v_add_f32_e32 v2, v0, v1
	s_nop 1
	s_waitcnt vmcnt(0)
	v_pk_mul_f32 v[0:1], v[68:69], v[12:13]
	s_nop 1
	v_add_f32_e32 v0, v2, v0
	v_add_f32_e32 v2, v0, v1
	s_nop 1
	v_pk_mul_f32 v[0:1], v[64:65], v[14:15]
	s_nop 0
	v_add_f32_e32 v16, 1.0, v18
	v_log_f32_e32 v16, v16
	s_nop 0
	v_mul_f32_e32 v16, 0x3f317218, v16
	s_nop 1
	v_add_f32_e32 v0, v2, v0
	v_sub_f32_e32 v16, v20, v16
	v_add_f32_e32 v2, v0, v1
	v_pk_mul_f32 v[0:1], v[72:73], v[8:9]
	v_mul_f32_e32 v16, 0x3d800000, v16
	v_add_f32_e32 v0, v2, v0
	v_cndmask_b32_e64 v16, 0, v16, s[44:45]
	v_add_f32_e32 v2, v0, v1
	v_add_f32_e32 v16, v19, v16
	v_pk_mul_f32 v[0:1], v[70:71], v[10:11]
	v_or_b32_e32 v185, 4, v187
	v_add_f32_e32 v0, v2, v0
	v_add_f32_e32 v0, v0, v1
	v_mul_f32_e64 v1, |v0|, s97
	v_exp_f32_e32 v2, v1
	v_min_f32_e32 v3, 0, v0
	v_cmp_gt_u32_e64 s[46:47], s10, v185
	v_or_b32_e32 v183, 5, v187
	s_nop 1
	v_cmp_gt_u32_e64 s[42:43], s10, v183
	v_or_b32_e32 v180, 6, v187
	s_nop 1
	v_cndmask_b32_e64 v0, 0, v185, s[46:47]
	s_nop 1
	v_add_u32_e32 v110, s54, v0
	s_nop 1
	v_ashrrev_i32_e32 v111, 31, v110
	s_nop 1
	v_lshlrev_b64 v[0:1], 6, v[110:111]
	v_lshl_add_u64 v[112:113], s[6:7], 0, v[0:1]
	global_load_dwordx4 v[8:11], v[112:113], off offset:16
	global_load_dwordx4 v[12:15], v[112:113], off
	global_load_dwordx4 v[36:39], v[112:113], off offset:48
	global_load_dwordx4 v[40:43], v[112:113], off offset:32
	s_nop 1
	v_cmp_gt_u32_e64 s[36:37], s10, v180
	v_or_b32_e32 v178, 7, v187
	s_nop 1
	v_cmp_gt_u32_e64 s[30:31], s10, v178
	s_waitcnt vmcnt(2)
	v_fma_f32 v12, v139, v12, v138
	v_fmac_f32_e32 v12, v140, v13
	s_nop 1
	v_fmac_f32_e32 v12, v141, v14
	v_fmac_f32_e32 v12, v143, v15
	s_nop 1
	v_fmac_f32_e32 v12, v142, v8
	v_fmac_f32_e32 v12, v48, v9
	v_add_f32_e32 v0, 1.0, v2
	v_log_f32_e32 v0, v0
	s_nop 0
	v_mul_f32_e32 v0, 0x3f317218, v0
	s_nop 1
	v_sub_f32_e32 v0, v3, v0
	v_pk_mul_f32 v[8:9], v[66:67], v[10:11]
	v_mul_f32_e32 v0, 0x3d800000, v0
	v_add_f32_e32 v8, v12, v8
	v_cndmask_b32_e64 v0, 0, v0, s[40:41]
	v_add_f32_e32 v10, v8, v9
	s_waitcnt vmcnt(0)
	v_pk_mul_f32 v[8:9], v[68:69], v[40:41]
	v_add_f32_e32 v46, v16, v0
	v_cndmask_b32_e64 v0, 0, v183, s[42:43]
	v_add_f32_e32 v8, v10, v8
	v_add_u32_e32 v114, s54, v0
	v_add_f32_e32 v10, v8, v9
	v_pk_mul_f32 v[8:9], v[64:65], v[42:43]
	v_ashrrev_i32_e32 v115, 31, v114
	v_add_f32_e32 v8, v10, v8
	v_lshlrev_b64 v[0:1], 6, v[114:115]
	v_add_f32_e32 v10, v8, v9
	v_pk_mul_f32 v[8:9], v[72:73], v[36:37]
	v_lshl_add_u64 v[118:119], s[6:7], 0, v[0:1]
	v_add_f32_e32 v8, v10, v8
	global_load_dwordx4 v[74:77], v[118:119], off offset:16
	global_load_dwordx4 v[78:81], v[118:119], off
	global_load_dwordx4 v[82:85], v[118:119], off offset:48
	global_load_dwordx4 v[86:89], v[118:119], off offset:32
	v_add_f32_e32 v10, v8, v9
	v_pk_mul_f32 v[8:9], v[70:71], v[38:39]
	v_cndmask_b32_e64 v0, 0, v180, s[36:37]
	v_add_f32_e32 v8, v10, v8
	v_add_f32_e32 v36, v8, v9
	v_mul_f32_e64 v8, |v36|, s97
	v_exp_f32_e32 v38, v8
	v_min_f32_e32 v39, 0, v36
	v_add_u32_e32 v116, s54, v0
	v_ashrrev_i32_e32 v117, 31, v116
	s_nop 1
	v_lshlrev_b64 v[0:1], 6, v[116:117]
	v_lshl_add_u64 v[122:123], s[6:7], 0, v[0:1]
	s_nop 1
	global_load_dwordx4 v[24:27], v[122:123], off offset:16
	global_load_dwordx4 v[28:31], v[122:123], off
	global_load_dwordx4 v[16:19], v[122:123], off offset:48
	global_load_dwordx4 v[20:23], v[122:123], off offset:32
	s_nop 1
	v_cndmask_b32_e64 v0, 0, v178, s[30:31]
	v_add_u32_e32 v120, s54, v0
	s_nop 1
	v_ashrrev_i32_e32 v121, 31, v120
	v_lshlrev_b64 v[0:1], 6, v[120:121]
	s_nop 1
	v_lshl_add_u64 v[124:125], s[6:7], 0, v[0:1]
	global_load_dwordx4 v[0:3], v[124:125], off offset:16
	global_load_dwordx4 v[4:7], v[124:125], off
	s_nop 1
	global_load_dwordx4 v[8:11], v[124:125], off offset:48
	global_load_dwordx4 v[12:15], v[124:125], off offset:32
	v_add_f32_e32 v36, 1.0, v38
	v_log_f32_e32 v36, v36
	s_nop 0
	v_mul_f32_e32 v36, 0x3f317218, v36
	s_nop 1
	v_sub_f32_e32 v36, v39, v36
	s_waitcnt vmcnt(10)
	v_fma_f32 v39, v139, v78, v138
	v_fmac_f32_e32 v39, v140, v79
	v_fmac_f32_e32 v39, v141, v80
	v_fmac_f32_e32 v39, v143, v81
	v_fmac_f32_e32 v39, v142, v74
	v_mul_f32_e32 v38, 0x3d800000, v36
	v_fmac_f32_e32 v39, v48, v75
	v_pk_mul_f32 v[36:37], v[66:67], v[76:77]
	s_waitcnt vmcnt(6)
	v_fma_f32 v28, v139, v28, v138
	v_add_f32_e32 v36, v39, v36
	v_add_f32_e32 v39, v36, v37
	v_pk_mul_f32 v[36:37], v[68:69], v[86:87]
	v_fmac_f32_e32 v28, v140, v29
	v_add_f32_e32 v36, v39, v36
	v_add_f32_e32 v39, v36, v37
	v_pk_mul_f32 v[36:37], v[64:65], v[88:89]
	v_fmac_f32_e32 v28, v141, v30
	v_add_f32_e32 v36, v39, v36
	v_add_f32_e32 v39, v36, v37
	v_pk_mul_f32 v[36:37], v[72:73], v[82:83]
	v_fmac_f32_e32 v28, v143, v31
	v_add_f32_e32 v36, v39, v36
	v_add_f32_e32 v39, v36, v37
	v_pk_mul_f32 v[36:37], v[70:71], v[84:85]
	v_fmac_f32_e32 v28, v142, v24
	v_add_f32_e32 v36, v39, v36
	v_add_f32_e32 v36, v36, v37
	v_mul_f32_e64 v37, |v36|, s97
	v_exp_f32_e32 v39, v37
	v_cndmask_b32_e64 v37, 0, v38, s[46:47]
	v_min_f32_e32 v40, 0, v36
	v_add_f32_e32 v38, v46, v37
	s_nop 1
	v_fmac_f32_e32 v28, v48, v25
	v_pk_mul_f32 v[24:25], v[66:67], v[26:27]
	s_nop 1
	v_add_f32_e32 v24, v28, v24
	s_nop 1
	v_add_f32_e32 v24, v24, v25
	s_waitcnt vmcnt(4)
	v_pk_mul_f32 v[20:21], v[68:69], v[20:21]
	s_nop 1
	v_add_f32_e32 v20, v24, v20
	s_nop 1
	v_add_f32_e32 v24, v20, v21
	v_pk_mul_f32 v[20:21], v[64:65], v[22:23]
	s_nop 1
	v_add_f32_e32 v20, v24, v20
	s_nop 1
	v_add_f32_e32 v20, v20, v21
	v_pk_mul_f32 v[16:17], v[72:73], v[16:17]
	s_nop 1
	v_add_f32_e32 v16, v20, v16
	s_nop 1
	v_add_f32_e32 v20, v16, v17
	v_pk_mul_f32 v[16:17], v[70:71], v[18:19]
	s_nop 1
	v_add_f32_e32 v16, v20, v16
	s_nop 1
	v_add_f32_e32 v16, v16, v17
	v_mul_f32_e64 v17, |v16|, s97
	s_nop 1
	v_exp_f32_e32 v18, v17
	v_min_f32_e32 v20, 0, v16
	s_nop 1
	s_waitcnt vmcnt(2)
	v_fma_f32 v4, v139, v4, v138
	v_add_f32_e32 v36, 1.0, v39
	v_log_f32_e32 v36, v36
	s_nop 0
	v_mul_f32_e32 v36, 0x3f317218, v36
	s_nop 1
	v_sub_f32_e32 v36, v40, v36
	v_mul_f32_e32 v36, 0x3d800000, v36
	v_cndmask_b32_e64 v17, 0, v36, s[42:43]
	v_add_f32_e32 v19, v38, v17
	s_nop 1
	v_fmac_f32_e32 v4, v140, v5
	v_fmac_f32_e32 v4, v141, v6
	s_nop 1
	v_fmac_f32_e32 v4, v143, v7
	s_nop 1
	v_fmac_f32_e32 v4, v142, v0
	s_nop 1
	v_fmac_f32_e32 v4, v48, v1
	v_pk_mul_f32 v[0:1], v[66:67], v[2:3]
	s_nop 1
	v_add_f32_e32 v0, v4, v0
	v_add_f32_e32 v2, v0, v1
	s_nop 1
	s_waitcnt vmcnt(0)
	v_pk_mul_f32 v[0:1], v[68:69], v[12:13]
	s_nop 1
	v_add_f32_e32 v0, v2, v0
	v_add_f32_e32 v2, v0, v1
	s_nop 1
	v_pk_mul_f32 v[0:1], v[64:65], v[14:15]
	s_nop 0
	v_add_f32_e32 v16, 1.0, v18
	v_log_f32_e32 v16, v16
	s_nop 0
	v_mul_f32_e32 v16, 0x3f317218, v16
	s_nop 1
	v_add_f32_e32 v0, v2, v0
	v_sub_f32_e32 v16, v20, v16
	v_add_f32_e32 v2, v0, v1
	v_pk_mul_f32 v[0:1], v[72:73], v[8:9]
	v_mul_f32_e32 v16, 0x3d800000, v16
	v_add_f32_e32 v0, v2, v0
	v_cndmask_b32_e64 v16, 0, v16, s[36:37]
	v_add_f32_e32 v2, v0, v1
	v_add_f32_e32 v16, v19, v16
	v_pk_mul_f32 v[0:1], v[70:71], v[10:11]
	v_or_b32_e32 v181, 8, v187
	v_add_f32_e32 v0, v2, v0
	v_add_f32_e32 v0, v0, v1
	v_mul_f32_e64 v1, |v0|, s97
	v_exp_f32_e32 v2, v1
	v_min_f32_e32 v3, 0, v0
	v_cmp_gt_u32_e64 s[38:39], s10, v181
	v_or_b32_e32 v179, 9, v187
	s_nop 1
	v_cmp_gt_u32_e64 s[34:35], s10, v179
	v_or_b32_e32 v176, 10, v187
	s_nop 1
	v_cndmask_b32_e64 v0, 0, v181, s[38:39]
	s_nop 1
	v_add_u32_e32 v94, s54, v0
	s_nop 1
	v_ashrrev_i32_e32 v95, 31, v94
	s_nop 1
	v_lshlrev_b64 v[0:1], 6, v[94:95]
	v_lshl_add_u64 v[96:97], s[6:7], 0, v[0:1]
	global_load_dwordx4 v[8:11], v[96:97], off offset:16
	global_load_dwordx4 v[12:15], v[96:97], off
	global_load_dwordx4 v[36:39], v[96:97], off offset:48
	global_load_dwordx4 v[40:43], v[96:97], off offset:32
	s_nop 1
	v_cmp_gt_u32_e64 s[26:27], s10, v176
	v_or_b32_e32 v146, 11, v187
	s_nop 1
	v_cmp_gt_u32_e64 s[22:23], s10, v146
	s_waitcnt vmcnt(2)
	v_fma_f32 v12, v139, v12, v138
	v_fmac_f32_e32 v12, v140, v13
	s_nop 1
	v_fmac_f32_e32 v12, v141, v14
	v_fmac_f32_e32 v12, v143, v15
	s_nop 1
	v_fmac_f32_e32 v12, v142, v8
	v_fmac_f32_e32 v12, v48, v9
	v_add_f32_e32 v0, 1.0, v2
	v_log_f32_e32 v0, v0
	s_nop 0
	v_mul_f32_e32 v0, 0x3f317218, v0
	s_nop 1
	v_sub_f32_e32 v0, v3, v0
	v_pk_mul_f32 v[8:9], v[66:67], v[10:11]
	v_mul_f32_e32 v0, 0x3d800000, v0
	v_add_f32_e32 v8, v12, v8
	v_cndmask_b32_e64 v0, 0, v0, s[30:31]
	v_add_f32_e32 v10, v8, v9
	s_waitcnt vmcnt(0)
	v_pk_mul_f32 v[8:9], v[68:69], v[40:41]
	v_add_f32_e32 v46, v16, v0
	v_cndmask_b32_e64 v0, 0, v179, s[34:35]
	v_add_f32_e32 v8, v10, v8
	v_add_u32_e32 v98, s54, v0
	v_add_f32_e32 v10, v8, v9
	v_pk_mul_f32 v[8:9], v[64:65], v[42:43]
	v_ashrrev_i32_e32 v99, 31, v98
	v_add_f32_e32 v8, v10, v8
	v_lshlrev_b64 v[0:1], 6, v[98:99]
	v_add_f32_e32 v10, v8, v9
	v_pk_mul_f32 v[8:9], v[72:73], v[36:37]
	v_lshl_add_u64 v[102:103], s[6:7], 0, v[0:1]
	v_add_f32_e32 v8, v10, v8
	global_load_dwordx4 v[74:77], v[102:103], off offset:16
	global_load_dwordx4 v[78:81], v[102:103], off
	global_load_dwordx4 v[82:85], v[102:103], off offset:48
	global_load_dwordx4 v[86:89], v[102:103], off offset:32
	v_add_f32_e32 v10, v8, v9
	v_pk_mul_f32 v[8:9], v[70:71], v[38:39]
	v_cndmask_b32_e64 v0, 0, v176, s[26:27]
	v_add_f32_e32 v8, v10, v8
	v_add_f32_e32 v36, v8, v9
	v_mul_f32_e64 v8, |v36|, s97
	v_exp_f32_e32 v38, v8
	v_min_f32_e32 v39, 0, v36
	v_add_u32_e32 v100, s54, v0
	v_ashrrev_i32_e32 v101, 31, v100
	s_nop 1
	v_lshlrev_b64 v[0:1], 6, v[100:101]
	v_lshl_add_u64 v[106:107], s[6:7], 0, v[0:1]
	s_nop 1
	global_load_dwordx4 v[24:27], v[106:107], off offset:16
	global_load_dwordx4 v[28:31], v[106:107], off
	global_load_dwordx4 v[16:19], v[106:107], off offset:48
	global_load_dwordx4 v[20:23], v[106:107], off offset:32
	s_nop 1
	v_cndmask_b32_e64 v0, 0, v146, s[22:23]
	v_add_u32_e32 v104, s54, v0
	s_nop 1
	v_ashrrev_i32_e32 v105, 31, v104
	v_lshlrev_b64 v[0:1], 6, v[104:105]
	s_nop 1
	v_lshl_add_u64 v[108:109], s[6:7], 0, v[0:1]
	global_load_dwordx4 v[0:3], v[108:109], off offset:16
	global_load_dwordx4 v[4:7], v[108:109], off
	s_nop 1
	global_load_dwordx4 v[8:11], v[108:109], off offset:48
	global_load_dwordx4 v[12:15], v[108:109], off offset:32
	v_add_f32_e32 v36, 1.0, v38
	v_log_f32_e32 v36, v36
	s_nop 0
	v_mul_f32_e32 v36, 0x3f317218, v36
	s_nop 1
	v_sub_f32_e32 v36, v39, v36
	s_waitcnt vmcnt(10)
	v_fma_f32 v39, v139, v78, v138
	v_fmac_f32_e32 v39, v140, v79
	v_fmac_f32_e32 v39, v141, v80
	v_fmac_f32_e32 v39, v143, v81
	v_fmac_f32_e32 v39, v142, v74
	v_mul_f32_e32 v38, 0x3d800000, v36
	v_fmac_f32_e32 v39, v48, v75
	v_pk_mul_f32 v[36:37], v[66:67], v[76:77]
	s_waitcnt vmcnt(6)
	v_fma_f32 v28, v139, v28, v138
	v_add_f32_e32 v36, v39, v36
	v_add_f32_e32 v39, v36, v37
	v_pk_mul_f32 v[36:37], v[68:69], v[86:87]
	v_fmac_f32_e32 v28, v140, v29
	v_add_f32_e32 v36, v39, v36
	v_add_f32_e32 v39, v36, v37
	v_pk_mul_f32 v[36:37], v[64:65], v[88:89]
	v_fmac_f32_e32 v28, v141, v30
	v_add_f32_e32 v36, v39, v36
	v_add_f32_e32 v39, v36, v37
	v_pk_mul_f32 v[36:37], v[72:73], v[82:83]
	v_fmac_f32_e32 v28, v143, v31
	v_add_f32_e32 v36, v39, v36
	v_add_f32_e32 v39, v36, v37
	v_pk_mul_f32 v[36:37], v[70:71], v[84:85]
	v_fmac_f32_e32 v28, v142, v24
	v_add_f32_e32 v36, v39, v36
	v_add_f32_e32 v36, v36, v37
	v_mul_f32_e64 v37, |v36|, s97
	v_exp_f32_e32 v39, v37
	v_cndmask_b32_e64 v37, 0, v38, s[38:39]
	v_min_f32_e32 v40, 0, v36
	v_add_f32_e32 v38, v46, v37
	s_nop 1
	v_fmac_f32_e32 v28, v48, v25
	v_pk_mul_f32 v[24:25], v[66:67], v[26:27]
	s_nop 1
	v_add_f32_e32 v24, v28, v24
	s_nop 1
	v_add_f32_e32 v24, v24, v25
	s_waitcnt vmcnt(4)
	v_pk_mul_f32 v[20:21], v[68:69], v[20:21]
	s_nop 1
	v_add_f32_e32 v20, v24, v20
	s_nop 1
	v_add_f32_e32 v24, v20, v21
	v_pk_mul_f32 v[20:21], v[64:65], v[22:23]
	s_nop 1
	v_add_f32_e32 v20, v24, v20
	s_nop 1
	v_add_f32_e32 v20, v20, v21
	v_pk_mul_f32 v[16:17], v[72:73], v[16:17]
	s_nop 1
	v_add_f32_e32 v16, v20, v16
	s_nop 1
	v_add_f32_e32 v20, v16, v17
	v_pk_mul_f32 v[16:17], v[70:71], v[18:19]
	s_nop 1
	v_add_f32_e32 v16, v20, v16
	s_nop 1
	v_add_f32_e32 v16, v16, v17
	v_mul_f32_e64 v17, |v16|, s97
	s_nop 1
	v_exp_f32_e32 v18, v17
	v_min_f32_e32 v20, 0, v16
	s_nop 1
	s_waitcnt vmcnt(2)
	v_fma_f32 v4, v139, v4, v138
	v_add_f32_e32 v36, 1.0, v39
	v_log_f32_e32 v36, v36
	s_nop 0
	v_mul_f32_e32 v36, 0x3f317218, v36
	s_nop 1
	v_sub_f32_e32 v36, v40, v36
	v_mul_f32_e32 v36, 0x3d800000, v36
	v_cndmask_b32_e64 v17, 0, v36, s[34:35]
	v_add_f32_e32 v19, v38, v17
	s_nop 1
	v_fmac_f32_e32 v4, v140, v5
	v_fmac_f32_e32 v4, v141, v6
	s_nop 1
	v_fmac_f32_e32 v4, v143, v7
	s_nop 1
	v_fmac_f32_e32 v4, v142, v0
	s_nop 1
	v_fmac_f32_e32 v4, v48, v1
	v_pk_mul_f32 v[0:1], v[66:67], v[2:3]
	s_nop 1
	v_add_f32_e32 v0, v4, v0
	v_add_f32_e32 v2, v0, v1
	s_nop 1
	s_waitcnt vmcnt(0)
	v_pk_mul_f32 v[0:1], v[68:69], v[12:13]
	s_nop 1
	v_add_f32_e32 v0, v2, v0
	v_add_f32_e32 v2, v0, v1
	s_nop 1
	v_pk_mul_f32 v[0:1], v[64:65], v[14:15]
	s_nop 0
	v_add_f32_e32 v16, 1.0, v18
	v_log_f32_e32 v16, v16
	s_nop 0
	v_mul_f32_e32 v16, 0x3f317218, v16
	s_nop 1
	v_add_f32_e32 v0, v2, v0
	v_sub_f32_e32 v16, v20, v16
	v_add_f32_e32 v2, v0, v1
	v_pk_mul_f32 v[0:1], v[72:73], v[8:9]
	v_mul_f32_e32 v16, 0x3d800000, v16
	v_add_f32_e32 v0, v2, v0
	v_cndmask_b32_e64 v16, 0, v16, s[26:27]
	v_add_f32_e32 v2, v0, v1
	v_add_f32_e32 v16, v19, v16
	v_pk_mul_f32 v[0:1], v[70:71], v[10:11]
	v_or_b32_e32 v177, 12, v187
	v_add_f32_e32 v0, v2, v0
	v_add_f32_e32 v0, v0, v1
	v_mul_f32_e64 v1, |v0|, s97
	v_exp_f32_e32 v2, v1
	v_min_f32_e32 v3, 0, v0
	v_cmp_gt_u32_e64 s[28:29], s10, v177
	v_or_b32_e32 v147, 13, v187
	s_nop 1
	v_cmp_gt_u32_e64 s[24:25], s10, v147
	v_or_b32_e32 v145, 14, v187
	s_nop 1
	v_cndmask_b32_e64 v0, 0, v177, s[28:29]
	s_nop 1
	v_add_u32_e32 v78, s54, v0
	s_nop 1
	v_ashrrev_i32_e32 v79, 31, v78
	s_nop 1
	v_lshlrev_b64 v[0:1], 6, v[78:79]
	v_lshl_add_u64 v[80:81], s[6:7], 0, v[0:1]
	global_load_dwordx4 v[8:11], v[80:81], off offset:16
	global_load_dwordx4 v[12:15], v[80:81], off
	global_load_dwordx4 v[36:39], v[80:81], off offset:48
	global_load_dwordx4 v[40:43], v[80:81], off offset:32
	s_nop 1
	v_cmp_gt_u32_e64 s[20:21], s10, v145
	v_or_b32_e32 v144, 15, v187
	s_nop 1
	s_waitcnt vmcnt(2)
	v_fma_f32 v12, v139, v12, v138
	v_fmac_f32_e32 v12, v140, v13
	s_nop 1
	v_fmac_f32_e32 v12, v141, v14
	v_fmac_f32_e32 v12, v143, v15
	s_nop 1
	v_fmac_f32_e32 v12, v142, v8
	v_fmac_f32_e32 v12, v48, v9
	v_add_f32_e32 v0, 1.0, v2
	v_log_f32_e32 v0, v0
	s_nop 0
	v_mul_f32_e32 v0, 0x3f317218, v0
	s_nop 1
	v_sub_f32_e32 v0, v3, v0
	v_pk_mul_f32 v[8:9], v[66:67], v[10:11]
	v_mul_f32_e32 v0, 0x3d800000, v0
	v_add_f32_e32 v8, v12, v8
	v_cndmask_b32_e64 v0, 0, v0, s[22:23]
	v_add_f32_e32 v10, v8, v9
	s_waitcnt vmcnt(0)
	v_pk_mul_f32 v[8:9], v[68:69], v[40:41]
	v_add_f32_e32 v46, v16, v0
	v_cndmask_b32_e64 v0, 0, v147, s[24:25]
	v_add_f32_e32 v8, v10, v8
	v_add_u32_e32 v82, s54, v0
	v_add_f32_e32 v10, v8, v9
	v_pk_mul_f32 v[8:9], v[64:65], v[42:43]
	v_ashrrev_i32_e32 v83, 31, v82
	v_add_f32_e32 v8, v10, v8
	v_lshlrev_b64 v[0:1], 6, v[82:83]
	v_add_f32_e32 v10, v8, v9
	v_pk_mul_f32 v[8:9], v[72:73], v[36:37]
	v_lshl_add_u64 v[86:87], s[6:7], 0, v[0:1]
	v_add_f32_e32 v8, v10, v8
	global_load_dwordx4 v[74:77], v[86:87], off offset:16
	global_load_dwordx4 v[188:191], v[86:87], off
	global_load_dwordx4 v[192:195], v[86:87], off offset:48
	global_load_dwordx4 v[196:199], v[86:87], off offset:32
	v_add_f32_e32 v10, v8, v9
	v_pk_mul_f32 v[8:9], v[70:71], v[38:39]
	v_cndmask_b32_e64 v0, 0, v145, s[20:21]
	v_add_f32_e32 v8, v10, v8
	v_add_f32_e32 v36, v8, v9
	v_mul_f32_e64 v8, |v36|, s97
	v_exp_f32_e32 v38, v8
	v_min_f32_e32 v39, 0, v36
	v_add_u32_e32 v84, s54, v0
	v_ashrrev_i32_e32 v85, 31, v84
	s_nop 1
	v_lshlrev_b64 v[0:1], 6, v[84:85]
	v_lshl_add_u64 v[90:91], s[6:7], 0, v[0:1]
	s_nop 1
	global_load_dwordx4 v[24:27], v[90:91], off offset:16
	global_load_dwordx4 v[28:31], v[90:91], off
	global_load_dwordx4 v[16:19], v[90:91], off offset:48
	global_load_dwordx4 v[20:23], v[90:91], off offset:32
	s_nop 1
	v_cmp_gt_u32_e32 vcc, s10, v144
	s_waitcnt vmcnt(2)
	v_fma_f32 v28, v139, v28, v138
	s_nop 1
	v_fmac_f32_e32 v28, v140, v29
	v_cndmask_b32_e32 v0, 0, v144, vcc
	s_nop 1
	v_fmac_f32_e32 v28, v141, v30
	v_add_u32_e32 v88, s54, v0
	v_add_f32_e32 v36, 1.0, v38
	v_log_f32_e32 v36, v36
	s_nop 0
	v_mul_f32_e32 v36, 0x3f317218, v36
	s_nop 1
	v_sub_f32_e32 v36, v39, v36
	v_fma_f32 v39, v139, v188, v138
	v_fmac_f32_e32 v39, v140, v189
	v_fmac_f32_e32 v39, v141, v190
	v_fmac_f32_e32 v39, v143, v191
	v_fmac_f32_e32 v39, v142, v74
	v_mul_f32_e32 v38, 0x3d800000, v36
	v_fmac_f32_e32 v39, v48, v75
	v_pk_mul_f32 v[36:37], v[66:67], v[76:77]
	v_fmac_f32_e32 v28, v143, v31
	v_add_f32_e32 v36, v39, v36
	v_add_f32_e32 v39, v36, v37
	v_pk_mul_f32 v[36:37], v[68:69], v[196:197]
	v_ashrrev_i32_e32 v89, 31, v88
	v_add_f32_e32 v36, v39, v36
	v_add_f32_e32 v39, v36, v37
	v_pk_mul_f32 v[36:37], v[64:65], v[198:199]
	v_fmac_f32_e32 v28, v142, v24
	v_add_f32_e32 v36, v39, v36
	v_add_f32_e32 v39, v36, v37
	v_pk_mul_f32 v[36:37], v[72:73], v[192:193]
	v_lshlrev_b64 v[0:1], 6, v[88:89]
	v_add_f32_e32 v36, v39, v36
	v_add_f32_e32 v39, v36, v37
	v_pk_mul_f32 v[36:37], v[70:71], v[194:195]
	v_fmac_f32_e32 v28, v48, v25
	v_add_f32_e32 v36, v39, v36
	v_add_f32_e32 v36, v36, v37
	v_mul_f32_e64 v37, |v36|, s97
	v_exp_f32_e32 v126, v37
	v_cndmask_b32_e64 v37, 0, v38, s[28:29]
	v_min_f32_e32 v188, 0, v36
	v_add_f32_e32 v127, v46, v37
	s_nop 1
	v_pk_mul_f32 v[24:25], v[66:67], v[26:27]
	v_lshl_add_u64 v[92:93], s[6:7], 0, v[0:1]
	s_nop 1
	v_add_f32_e32 v24, v28, v24
	s_nop 1
	global_load_dwordx4 v[0:3], v[92:93], off offset:16
	global_load_dwordx4 v[4:7], v[92:93], off
	s_nop 1
	v_add_f32_e32 v24, v24, v25
	s_nop 1
	s_waitcnt vmcnt(2)
	v_pk_mul_f32 v[20:21], v[68:69], v[20:21]
	s_nop 1
	v_add_f32_e32 v20, v24, v20
	s_nop 1
	v_add_f32_e32 v24, v20, v21
	s_nop 1
	v_pk_mul_f32 v[20:21], v[64:65], v[22:23]
	s_nop 1
	v_add_f32_e32 v20, v24, v20
	s_nop 1
	v_add_f32_e32 v20, v20, v21
	v_pk_mul_f32 v[16:17], v[72:73], v[16:17]
	s_nop 1
	v_add_f32_e32 v16, v20, v16
	s_nop 1
	v_add_f32_e32 v20, v16, v17
	v_pk_mul_f32 v[16:17], v[70:71], v[18:19]
	global_load_dwordx4 v[8:11], v[92:93], off offset:48
	global_load_dwordx4 v[12:15], v[92:93], off offset:32
	s_nop 1
	v_add_f32_e32 v16, v20, v16
	s_nop 1
	v_add_f32_e32 v16, v16, v17
	v_mul_f32_e64 v17, |v16|, s97
	s_nop 1
	v_exp_f32_e32 v30, v17
	s_waitcnt vmcnt(2)
	v_fma_f32 v4, v139, v4, v138
	s_nop 1
	v_fmac_f32_e32 v4, v140, v5
	v_fmac_f32_e32 v4, v141, v6
	v_add_f32_e32 v36, 1.0, v126
	v_log_f32_e32 v36, v36
	s_nop 0
	v_mul_f32_e32 v36, 0x3f317218, v36
	s_nop 1
	v_sub_f32_e32 v36, v188, v36
	v_mul_f32_e32 v36, 0x3d800000, v36
	v_cndmask_b32_e64 v17, 0, v36, s[24:25]
	v_min_f32_e32 v36, 0, v16
	s_nop 1
	v_add_f32_e32 v31, v127, v17
	s_nop 1
	v_fmac_f32_e32 v4, v143, v7
	v_fmac_f32_e32 v4, v142, v0
	s_nop 1
	v_fmac_f32_e32 v4, v48, v1
	s_nop 1
	v_pk_mul_f32 v[0:1], v[66:67], v[2:3]
	s_nop 1
	v_add_f32_e32 v0, v4, v0
	s_nop 1
	v_add_f32_e32 v2, v0, v1
	s_nop 1
	s_waitcnt vmcnt(0)
	v_pk_mul_f32 v[0:1], v[68:69], v[12:13]
	s_nop 1
	v_add_f32_e32 v0, v2, v0
	v_add_f32_e32 v2, v0, v1
	s_nop 1
	v_pk_mul_f32 v[0:1], v[64:65], v[14:15]
	s_nop 0
	s_nop 1
	v_add_f32_e32 v0, v2, v0
	v_add_f32_e32 v2, v0, v1
	v_add_f32_e32 v16, 1.0, v30
	v_log_f32_e32 v16, v16
	s_nop 0
	v_mul_f32_e32 v16, 0x3f317218, v16
	s_nop 1
	v_sub_f32_e32 v16, v36, v16
	v_pk_mul_f32 v[0:1], v[72:73], v[8:9]
	v_mul_f32_e32 v16, 0x3d800000, v16
	v_add_f32_e32 v0, v2, v0
	v_cndmask_b32_e64 v16, 0, v16, s[20:21]
	v_add_f32_e32 v2, v0, v1
	v_add_f32_e32 v16, v31, v16
	v_pk_mul_f32 v[0:1], v[70:71], v[10:11]
	s_nop 0
	v_add_f32_e32 v0, v2, v0
	v_add_f32_e32 v0, v0, v1
	v_mul_f32_e64 v1, |v0|, s97
	v_exp_f32_e32 v14, v1
	v_min_f32_e32 v15, 0, v0
	s_barrier
	s_nop 1
	s_nop 1
	s_nop 1
	s_nop 0
	s_nop 1
	s_nop 0
	s_nop 1
	s_nop 0
	s_nop 1
	s_nop 0
	s_nop 1
	s_nop 0
	s_nop 1
	s_nop 1
	s_nop 1
	s_nop 1
	s_nop 1
	s_nop 1
	v_add_f32_e32 v0, 1.0, v14
	v_log_f32_e32 v0, v0
	s_nop 0
	v_mul_f32_e32 v0, 0x3f317218, v0
	s_nop 1
	v_sub_f32_e32 v0, v15, v0
	v_mul_f32_e32 v0, 0x3d800000, v0
	v_cndmask_b32_e32 v0, 0, v0, vcc
	v_add_f32_e32 v0, v16, v0
	ds_write_b32 v151, v0
	s_waitcnt lgkmcnt(0)
	s_barrier
	ds_read2st64_b32 v[2:3], v159 offset1:1
	ds_read2st64_b32 v[0:1], v159 offset0:2 offset1:3
	s_waitcnt lgkmcnt(1)
	v_add_f32_e32 v2, 0, v2
	s_mov_b64 s[52:53], exec
	v_readlane_b32 s10, v252, 33
	v_readlane_b32 s11, v252, 34
	s_and_b64 s[10:11], s[52:53], s[10:11]
	s_mov_b64 exec, s[10:11]
	s_cbranch_execz .LBB0_278
	s_lshl_b32 s10, s17, 6
	v_add_f32_e32 v4, v2, v3
	s_or_b32 s33, s10, s18
	s_add_i32 s55, s17, 0x3f0
	s_waitcnt lgkmcnt(0)
	v_add_f32_e32 v4, v4, v0
	s_and_b64 s[10:11], s[12:13], exec
	v_add_f32_e32 v4, v4, v1
	s_cselect_b32 s10, s33, s55
	v_mul_f32_e32 v4, 0x3fb8aa3b, v4
	s_mul_hi_i32 s11, s10, 0xc00
	s_mulk_i32 s10, 0xc00
	v_readlane_b32 s33, v252, 44
	v_exp_f32_e32 v4, v4
	s_add_u32 s10, s33, s10
	v_readlane_b32 s33, v252, 45
	s_addc_u32 s11, s33, s11
	s_lshl_b32 s33, s4, 2
	s_add_u32 s10, s10, s33
	v_readlane_b32 s33, v252, 35
	s_addc_u32 s11, s11, 0
	v_lshlrev_b32_e32 v5, 2, v154
	global_store_dword v5, v4, s[10:11]
.LBB0_278:
	s_or_b64 exec, exec, s[52:53]
	v_readlane_b32 s10, v252, 33
	v_readlane_b32 s11, v252, 34
	global_load_dwordx4 v[190:193], v[34:35], off offset:16
	global_load_dwordx4 v[194:197], v[34:35], off
	global_load_dwordx4 v[198:201], v[34:35], off offset:48
	global_load_dwordx4 v[206:209], v[34:35], off offset:32
	v_cndmask_b32_e64 v2, v2, 0, s[10:11]
	v_readlane_b32 s10, v252, 36
	v_add_f32_e32 v3, v3, v2
	v_readlane_b32 s11, v252, 37
	s_lshl_b32 s4, s4, 1
	v_lshl_add_u64 v[126:127], v[54:55], 0, s[4:5]
	v_cndmask_b32_e64 v2, v2, v3, s[10:11]
	v_readlane_b32 s10, v252, 38
	s_waitcnt lgkmcnt(0)
	v_add_f32_e32 v0, v0, v2
	v_readlane_b32 s11, v252, 39
	v_lshl_add_u64 v[74:75], v[56:57], 0, s[4:5]
	v_lshlrev_b64 v[128:129], 9, v[128:129]
	v_cndmask_b32_e64 v0, v2, v0, s[10:11]
	v_readlane_b32 s10, v252, 40
	v_add_f32_e32 v1, v1, v0
	v_readlane_b32 s11, v252, 41
	v_lshl_add_u64 v[76:77], v[58:59], 0, s[4:5]
	s_nop 0
	v_cndmask_b32_e64 v202, v0, v1, s[10:11]
	v_lshlrev_b64 v[0:1], 9, v[32:33]
	v_lshl_add_u64 v[2:3], v[126:127], 0, v[0:1]
	v_lshl_add_u64 v[0:1], v[74:75], 0, v[0:1]
	global_load_ushort v188, v[2:3], off
	global_load_ushort v189, v[0:1], off
	global_load_dwordx4 v[32:35], v[44:45], off offset:48
	global_load_dwordx4 v[36:39], v[44:45], off offset:32
	global_load_dwordx4 v[40:43], v[44:45], off offset:16
	s_nop 0
	global_load_dwordx4 v[44:47], v[44:45], off
	v_lshlrev_b64 v[0:1], 9, v[136:137]
	v_lshl_add_u64 v[2:3], v[126:127], 0, v[0:1]
	v_lshl_add_u64 v[0:1], v[74:75], 0, v[0:1]
	global_load_ushort v136, v[2:3], off
	global_load_ushort v137, v[0:1], off
	global_load_dwordx4 v[16:19], v[134:135], off offset:48
	global_load_dwordx4 v[20:23], v[134:135], off offset:32
	global_load_dwordx4 v[24:27], v[134:135], off offset:16
	global_load_dwordx4 v[28:31], v[134:135], off
	v_lshlrev_b64 v[0:1], 9, v[132:133]
	v_lshl_add_u64 v[2:3], v[126:127], 0, v[0:1]
	v_lshl_add_u64 v[0:1], v[74:75], 0, v[0:1]
	global_load_ushort v132, v[2:3], off
	global_load_ushort v133, v[0:1], off
	s_nop 0
	global_load_dwordx4 v[0:3], v[130:131], off offset:48
	global_load_dwordx4 v[4:7], v[130:131], off offset:32
	global_load_dwordx4 v[8:11], v[130:131], off offset:16
	global_load_dwordx4 v[12:15], v[130:131], off
	v_lshl_add_u64 v[130:131], v[126:127], 0, v[128:129]
	v_lshl_add_u64 v[128:129], v[74:75], 0, v[128:129]
	global_load_ushort v63, v[130:131], off
	s_nop 0
	global_load_ushort v128, v[128:129], off
	s_waitcnt vmcnt(23)
	v_pk_mul_f32 v[130:131], v[66:67], v[192:193]
	s_waitcnt vmcnt(22)
	v_fma_f32 v129, v139, v194, v138
	v_fmac_f32_e32 v129, v140, v195
	v_fmac_f32_e32 v129, v141, v196
	v_fmac_f32_e32 v129, v143, v197
	v_fmac_f32_e32 v129, v142, v190
	v_fmac_f32_e32 v129, v48, v191
	v_add_f32_e32 v129, v129, v130
	v_add_f32_e32 v129, v129, v131
	s_waitcnt vmcnt(20)
	v_pk_mul_f32 v[130:131], v[68:69], v[206:207]
	s_nop 0
	v_add_f32_e32 v129, v129, v130
	v_add_f32_e32 v129, v129, v131
	v_pk_mul_f32 v[130:131], v[64:65], v[208:209]
	s_nop 0
	v_add_f32_e32 v129, v129, v130
	v_add_f32_e32 v129, v129, v131
	v_pk_mul_f32 v[130:131], v[72:73], v[198:199]
	s_nop 0
	v_add_f32_e32 v129, v129, v130
	v_add_f32_e32 v129, v129, v131
	v_pk_mul_f32 v[130:131], v[70:71], v[200:201]
	s_nop 0
	v_add_f32_e32 v129, v129, v130
	v_add_f32_e32 v129, v129, v131
	v_mul_f32_e64 v130, |v129|, s97
	v_exp_f32_e32 v134, v130
	v_min_f32_e32 v129, 0, v129
	s_nop 1
	s_nop 1
	s_nop 1
	s_nop 1
	s_nop 1
	s_nop 1
	s_nop 1
	s_nop 1
	s_nop 1
	s_nop 1
	v_add_f32_e32 v130, 1.0, v134
	v_log_f32_e32 v130, v130
	s_nop 0
	v_mul_f32_e32 v130, 0x3f317218, v130
	s_nop 1
	v_sub_f32_e32 v129, v129, v130
	v_mul_f32_e32 v129, 0x3d800000, v129
	v_cndmask_b32_e64 v129, 0, v129, s[50:51]
	v_add_f32_e32 v129, v202, v129
	s_and_saveexec_b64 s[52:53], s[50:51]
	s_cbranch_execz .LBB0_280
	v_mul_f32_e32 v135, 0x3fb8aa3b, v129
	v_exp_f32_e32 v135, v135
	v_add_u32_e32 v130, s54, v187
	v_ashrrev_i32_e32 v131, 31, v130
	s_waitcnt vmcnt(18)
	v_lshlrev_b32_e32 v134, 16, v189
	v_mul_f32_e32 v134, v135, v134
	v_lshlrev_b64 v[130:131], 9, v[130:131]
	v_cvt_pk_bf16_f32 v187, v134, v49
	v_lshl_add_u64 v[134:135], v[74:75], 0, v[130:131]
	global_store_short v[134:135], v187, off
	v_mul_f32_e32 v134, 0xbfb8aa3b, v129
	v_exp_f32_e32 v134, v134
	v_lshlrev_b32_e32 v188, 16, v188
	v_lshl_add_u64 v[130:131], v[76:77], 0, v[130:131]
	v_mul_f32_e32 v134, v134, v188
	v_cvt_pk_bf16_f32 v134, v134, v49
	global_store_short v[130:131], v134, off
.LBB0_280:
	s_or_b64 exec, exec, s[52:53]
	s_waitcnt vmcnt(14)
	v_fma_f32 v44, v139, v44, v138
	v_fmac_f32_e32 v44, v140, v45
	v_fmac_f32_e32 v44, v141, v46
	v_fmac_f32_e32 v44, v143, v47
	v_fmac_f32_e32 v44, v142, v40
	v_fmac_f32_e32 v44, v48, v41
	v_pk_mul_f32 v[40:41], v[66:67], v[42:43]
	v_pk_mul_f32 v[36:37], v[68:69], v[36:37]
	v_add_f32_e32 v40, v44, v40
	v_add_f32_e32 v40, v40, v41
	v_add_f32_e32 v36, v40, v36
	v_add_f32_e32 v40, v36, v37
	v_pk_mul_f32 v[36:37], v[64:65], v[38:39]
	v_pk_mul_f32 v[32:33], v[72:73], v[32:33]
	v_add_f32_e32 v36, v40, v36
	v_add_f32_e32 v36, v36, v37
	v_add_f32_e32 v32, v36, v32
	v_add_f32_e32 v36, v32, v33
	v_pk_mul_f32 v[32:33], v[70:71], v[34:35]
	s_nop 0
	v_add_f32_e32 v32, v36, v32
	v_add_f32_e32 v32, v32, v33
	v_mul_f32_e64 v33, |v32|, s97
	v_exp_f32_e32 v34, v33
	v_min_f32_e32 v35, 0, v32
	s_nop 1
	s_nop 1
	s_nop 1
	s_nop 1
	s_nop 1
	s_nop 1
	s_nop 1
	s_nop 1
	s_nop 1
	s_nop 1
	v_add_f32_e32 v32, 1.0, v34
	v_log_f32_e32 v32, v32
	s_nop 0
	v_mul_f32_e32 v32, 0x3f317218, v32
	s_nop 1
	v_sub_f32_e32 v32, v35, v32
	v_mul_f32_e32 v32, 0x3d800000, v32
	v_cndmask_b32_e64 v32, 0, v32, s[48:49]
	v_add_f32_e32 v32, v129, v32
	s_and_saveexec_b64 s[50:51], s[48:49]
	s_cbranch_execz .LBB0_282
	v_mul_f32_e32 v37, 0x3fb8aa3b, v32
	v_exp_f32_e32 v37, v37
	v_add_u32_e32 v34, s54, v186
	v_ashrrev_i32_e32 v35, 31, v34
	s_waitcnt vmcnt(12)
	v_lshlrev_b32_e32 v36, 16, v137
	v_mul_f32_e32 v36, v37, v36
	v_lshlrev_b64 v[34:35], 9, v[34:35]
	v_cvt_pk_bf16_f32 v38, v36, v49
	v_lshl_add_u64 v[36:37], v[74:75], 0, v[34:35]
	global_store_short v[36:37], v38, off
	v_mul_f32_e32 v36, 0xbfb8aa3b, v32
	v_exp_f32_e32 v36, v36
	v_lshlrev_b32_e32 v33, 16, v136
	v_lshl_add_u64 v[34:35], v[76:77], 0, v[34:35]
	v_mul_f32_e32 v33, v36, v33
	v_cvt_pk_bf16_f32 v33, v33, v49
	global_store_short v[34:35], v33, off
.LBB0_282:
	s_or_b64 exec, exec, s[50:51]
	s_waitcnt vmcnt(8)
	v_fma_f32 v28, v139, v28, v138
	v_fmac_f32_e32 v28, v140, v29
	v_fmac_f32_e32 v28, v141, v30
	v_fmac_f32_e32 v28, v143, v31
	v_fmac_f32_e32 v28, v142, v24
	v_fmac_f32_e32 v28, v48, v25
	v_pk_mul_f32 v[24:25], v[66:67], v[26:27]
	v_pk_mul_f32 v[20:21], v[68:69], v[20:21]
	v_add_f32_e32 v24, v28, v24
	v_add_f32_e32 v24, v24, v25
	v_add_f32_e32 v20, v24, v20
	v_add_f32_e32 v24, v20, v21
	v_pk_mul_f32 v[20:21], v[64:65], v[22:23]
	v_pk_mul_f32 v[16:17], v[72:73], v[16:17]
	v_add_f32_e32 v20, v24, v20
	v_add_f32_e32 v20, v20, v21
	v_add_f32_e32 v16, v20, v16
	v_add_f32_e32 v20, v16, v17
	v_pk_mul_f32 v[16:17], v[70:71], v[18:19]
	s_nop 0
	v_add_f32_e32 v16, v20, v16
	v_add_f32_e32 v16, v16, v17
	v_mul_f32_e64 v17, |v16|, s97
	v_exp_f32_e32 v18, v17
	v_min_f32_e32 v19, 0, v16
	s_nop 1
	s_nop 1
	s_nop 1
	s_nop 1
	s_nop 1
	s_nop 1
	s_nop 1
	s_nop 1
	s_nop 1
	s_nop 1
	v_add_f32_e32 v16, 1.0, v18
	v_log_f32_e32 v16, v16
	s_nop 0
	v_mul_f32_e32 v16, 0x3f317218, v16
	s_nop 1
	v_sub_f32_e32 v16, v19, v16
	v_mul_f32_e32 v16, 0x3d800000, v16
	v_cndmask_b32_e64 v16, 0, v16, s[44:45]
	v_add_f32_e32 v16, v32, v16
	s_and_saveexec_b64 s[48:49], s[44:45]
	s_cbranch_execz .LBB0_284
	v_mul_f32_e32 v21, 0x3fb8aa3b, v16
	v_exp_f32_e32 v21, v21
	v_add_u32_e32 v18, s54, v184
	v_ashrrev_i32_e32 v19, 31, v18
	s_waitcnt vmcnt(6)
	v_lshlrev_b32_e32 v20, 16, v133
	v_mul_f32_e32 v20, v21, v20
	v_lshlrev_b64 v[18:19], 9, v[18:19]
	v_cvt_pk_bf16_f32 v22, v20, v49
	v_lshl_add_u64 v[20:21], v[74:75], 0, v[18:19]
	global_store_short v[20:21], v22, off
	v_mul_f32_e32 v20, 0xbfb8aa3b, v16
	v_exp_f32_e32 v20, v20
	v_lshlrev_b32_e32 v17, 16, v132
	v_lshl_add_u64 v[18:19], v[76:77], 0, v[18:19]
	v_mul_f32_e32 v17, v20, v17
	v_cvt_pk_bf16_f32 v17, v17, v49
	global_store_short v[18:19], v17, off
.LBB0_284:
	s_or_b64 exec, exec, s[48:49]
	s_waitcnt vmcnt(2)
	v_fma_f32 v12, v139, v12, v138
	v_fmac_f32_e32 v12, v140, v13
	v_fmac_f32_e32 v12, v141, v14
	v_fmac_f32_e32 v12, v143, v15
	v_fmac_f32_e32 v12, v142, v8
	v_fmac_f32_e32 v12, v48, v9
	v_pk_mul_f32 v[8:9], v[66:67], v[10:11]
	v_pk_mul_f32 v[4:5], v[68:69], v[4:5]
	v_add_f32_e32 v8, v12, v8
	v_add_f32_e32 v8, v8, v9
	v_add_f32_e32 v4, v8, v4
	v_add_f32_e32 v8, v4, v5
	v_pk_mul_f32 v[4:5], v[64:65], v[6:7]
	v_pk_mul_f32 v[0:1], v[72:73], v[0:1]
	v_add_f32_e32 v4, v8, v4
	v_add_f32_e32 v4, v4, v5
	v_add_f32_e32 v0, v4, v0
	v_add_f32_e32 v4, v0, v1
	v_pk_mul_f32 v[0:1], v[70:71], v[2:3]
	s_nop 0
	v_add_f32_e32 v0, v4, v0
	v_add_f32_e32 v0, v0, v1
	v_mul_f32_e64 v1, |v0|, s97
	v_exp_f32_e32 v2, v1
	v_min_f32_e32 v3, 0, v0
	s_nop 1
	s_nop 1
	s_nop 1
	s_nop 1
	s_nop 1
	s_nop 1
	s_nop 1
	s_nop 1
	s_nop 1
	s_nop 1
	v_add_f32_e32 v0, 1.0, v2
	v_log_f32_e32 v0, v0
	s_nop 0
	v_mul_f32_e32 v0, 0x3f317218, v0
	s_nop 1
	v_sub_f32_e32 v0, v3, v0
	v_mul_f32_e32 v0, 0x3d800000, v0
	v_cndmask_b32_e64 v0, 0, v0, s[40:41]
	v_add_f32_e32 v129, v16, v0
	s_and_saveexec_b64 s[44:45], s[40:41]
	s_cbranch_execz .LBB0_286
	v_mul_f32_e32 v3, 0x3fb8aa3b, v129
	v_exp_f32_e32 v3, v3
	v_add_u32_e32 v0, s54, v182
	v_ashrrev_i32_e32 v1, 31, v0
	s_waitcnt vmcnt(0)
	v_lshlrev_b32_e32 v2, 16, v128
	v_mul_f32_e32 v2, v3, v2
	v_lshlrev_b64 v[0:1], 9, v[0:1]
	v_cvt_pk_bf16_f32 v5, v2, v49
	v_lshl_add_u64 v[2:3], v[74:75], 0, v[0:1]
	global_store_short v[2:3], v5, off
	v_mul_f32_e32 v2, 0xbfb8aa3b, v129
	v_exp_f32_e32 v2, v2
	v_lshlrev_b32_e32 v4, 16, v63
	v_lshl_add_u64 v[0:1], v[76:77], 0, v[0:1]
	v_mul_f32_e32 v2, v2, v4
	v_cvt_pk_bf16_f32 v2, v2, v49
	global_store_short v[0:1], v2, off
.LBB0_286:
	s_or_b64 exec, exec, s[44:45]
	global_load_dwordx4 v[132:135], v[112:113], off offset:16
	global_load_dwordx4 v[186:189], v[112:113], off
	global_load_dwordx4 v[190:193], v[112:113], off offset:48
	global_load_dwordx4 v[194:197], v[112:113], off offset:32
	v_lshlrev_b64 v[0:1], 9, v[110:111]
	v_lshl_add_u64 v[2:3], v[126:127], 0, v[0:1]
	v_lshl_add_u64 v[0:1], v[74:75], 0, v[0:1]
	global_load_ushort v128, v[2:3], off
	global_load_ushort v130, v[0:1], off
	global_load_dwordx4 v[32:35], v[118:119], off offset:48
	global_load_dwordx4 v[36:39], v[118:119], off offset:32
	global_load_dwordx4 v[40:43], v[118:119], off offset:16
	global_load_dwordx4 v[44:47], v[118:119], off
	v_lshlrev_b64 v[0:1], 9, v[114:115]
	v_lshl_add_u64 v[2:3], v[126:127], 0, v[0:1]
	v_lshl_add_u64 v[0:1], v[74:75], 0, v[0:1]
	global_load_ushort v113, v[2:3], off
	global_load_ushort v114, v[0:1], off
	global_load_dwordx4 v[16:19], v[122:123], off offset:48
	global_load_dwordx4 v[20:23], v[122:123], off offset:32
	global_load_dwordx4 v[24:27], v[122:123], off offset:16
	global_load_dwordx4 v[28:31], v[122:123], off
	v_lshlrev_b64 v[0:1], 9, v[116:117]
	v_lshl_add_u64 v[2:3], v[126:127], 0, v[0:1]
	v_lshl_add_u64 v[0:1], v[74:75], 0, v[0:1]
	global_load_ushort v111, v[2:3], off
	global_load_ushort v112, v[0:1], off
	s_nop 0
	global_load_dwordx4 v[0:3], v[124:125], off offset:48
	global_load_dwordx4 v[4:7], v[124:125], off offset:32
	global_load_dwordx4 v[8:11], v[124:125], off offset:16
	global_load_dwordx4 v[12:15], v[124:125], off
	v_lshlrev_b64 v[116:117], 9, v[120:121]
	v_lshl_add_u64 v[118:119], v[126:127], 0, v[116:117]
	v_lshl_add_u64 v[116:117], v[74:75], 0, v[116:117]
	global_load_ushort v63, v[118:119], off
	global_load_ushort v110, v[116:117], off
	s_waitcnt vmcnt(23)
	v_pk_mul_f32 v[116:117], v[66:67], v[134:135]
	s_waitcnt vmcnt(22)
	v_fma_f32 v115, v139, v186, v138
	v_fmac_f32_e32 v115, v140, v187
	v_fmac_f32_e32 v115, v141, v188
	v_fmac_f32_e32 v115, v143, v189
	v_fmac_f32_e32 v115, v142, v132
	v_fmac_f32_e32 v115, v48, v133
	v_add_f32_e32 v115, v115, v116
	v_add_f32_e32 v115, v115, v117
	s_waitcnt vmcnt(20)
	v_pk_mul_f32 v[116:117], v[68:69], v[194:195]
	s_nop 0
	v_add_f32_e32 v115, v115, v116
	v_add_f32_e32 v115, v115, v117
	v_pk_mul_f32 v[116:117], v[64:65], v[196:197]
	s_nop 0
	v_add_f32_e32 v115, v115, v116
	v_add_f32_e32 v115, v115, v117
	v_pk_mul_f32 v[116:117], v[72:73], v[190:191]
	s_nop 0
	v_add_f32_e32 v115, v115, v116
	v_add_f32_e32 v115, v115, v117
	v_pk_mul_f32 v[116:117], v[70:71], v[192:193]
	s_nop 0
	v_add_f32_e32 v115, v115, v116
	v_add_f32_e32 v115, v115, v117
	v_mul_f32_e64 v116, |v115|, s97
	v_exp_f32_e32 v118, v116
	v_min_f32_e32 v115, 0, v115
	s_nop 1
	s_nop 1
	s_nop 1
	s_nop 1
	s_nop 1
	s_nop 1
	s_nop 1
	s_nop 1
	s_nop 1
	s_nop 1
	v_add_f32_e32 v116, 1.0, v118
	v_log_f32_e32 v116, v116
	s_nop 0
	v_mul_f32_e32 v116, 0x3f317218, v116
	s_nop 1
	v_sub_f32_e32 v115, v115, v116
	v_mul_f32_e32 v115, 0x3d800000, v115
	v_cndmask_b32_e64 v115, 0, v115, s[46:47]
	v_add_f32_e32 v115, v129, v115
	s_and_saveexec_b64 s[40:41], s[46:47]
	s_cbranch_execz .LBB0_288
	v_mul_f32_e32 v119, 0x3fb8aa3b, v115
	v_exp_f32_e32 v119, v119
	v_add_u32_e32 v116, s54, v185
	v_ashrrev_i32_e32 v117, 31, v116
	s_waitcnt vmcnt(18)
	v_lshlrev_b32_e32 v118, 16, v130
	v_mul_f32_e32 v118, v119, v118
	v_lshlrev_b64 v[116:117], 9, v[116:117]
	v_cvt_pk_bf16_f32 v121, v118, v49
	v_lshl_add_u64 v[118:119], v[74:75], 0, v[116:117]
	global_store_short v[118:119], v121, off
	v_mul_f32_e32 v118, 0xbfb8aa3b, v115
	v_exp_f32_e32 v118, v118
	v_lshlrev_b32_e32 v120, 16, v128
	v_lshl_add_u64 v[116:117], v[76:77], 0, v[116:117]
	v_mul_f32_e32 v118, v118, v120
	v_cvt_pk_bf16_f32 v118, v118, v49
	global_store_short v[116:117], v118, off
.LBB0_288:
	s_or_b64 exec, exec, s[40:41]
	s_waitcnt vmcnt(14)
	v_fma_f32 v44, v139, v44, v138
	v_fmac_f32_e32 v44, v140, v45
	v_fmac_f32_e32 v44, v141, v46
	v_fmac_f32_e32 v44, v143, v47
	v_fmac_f32_e32 v44, v142, v40
	v_fmac_f32_e32 v44, v48, v41
	v_pk_mul_f32 v[40:41], v[66:67], v[42:43]
	v_pk_mul_f32 v[36:37], v[68:69], v[36:37]
	v_add_f32_e32 v40, v44, v40
	v_add_f32_e32 v40, v40, v41
	v_add_f32_e32 v36, v40, v36
	v_add_f32_e32 v40, v36, v37
	v_pk_mul_f32 v[36:37], v[64:65], v[38:39]
	v_pk_mul_f32 v[32:33], v[72:73], v[32:33]
	v_add_f32_e32 v36, v40, v36
	v_add_f32_e32 v36, v36, v37
	v_add_f32_e32 v32, v36, v32
	v_add_f32_e32 v36, v32, v33
	v_pk_mul_f32 v[32:33], v[70:71], v[34:35]
	s_nop 0
	v_add_f32_e32 v32, v36, v32
	v_add_f32_e32 v32, v32, v33
	v_mul_f32_e64 v33, |v32|, s97
	v_exp_f32_e32 v34, v33
	v_min_f32_e32 v35, 0, v32
	s_nop 1
	s_nop 1
	s_nop 1
	s_nop 1
	s_nop 1
	s_nop 1
	s_nop 1
	s_nop 1
	s_nop 1
	s_nop 1
	v_add_f32_e32 v32, 1.0, v34
	v_log_f32_e32 v32, v32
	s_nop 0
	v_mul_f32_e32 v32, 0x3f317218, v32
	s_nop 1
	v_sub_f32_e32 v32, v35, v32
	v_mul_f32_e32 v32, 0x3d800000, v32
	v_cndmask_b32_e64 v32, 0, v32, s[42:43]
	v_add_f32_e32 v32, v115, v32
	s_and_saveexec_b64 s[40:41], s[42:43]
	s_cbranch_execz .LBB0_290
	v_mul_f32_e32 v37, 0x3fb8aa3b, v32
	v_exp_f32_e32 v37, v37
	v_add_u32_e32 v34, s54, v183
	v_ashrrev_i32_e32 v35, 31, v34
	s_waitcnt vmcnt(12)
	v_lshlrev_b32_e32 v36, 16, v114
	v_mul_f32_e32 v36, v37, v36
	v_lshlrev_b64 v[34:35], 9, v[34:35]
	v_cvt_pk_bf16_f32 v38, v36, v49
	v_lshl_add_u64 v[36:37], v[74:75], 0, v[34:35]
	global_store_short v[36:37], v38, off
	v_mul_f32_e32 v36, 0xbfb8aa3b, v32
	v_exp_f32_e32 v36, v36
	v_lshlrev_b32_e32 v33, 16, v113
	v_lshl_add_u64 v[34:35], v[76:77], 0, v[34:35]
	v_mul_f32_e32 v33, v36, v33
	v_cvt_pk_bf16_f32 v33, v33, v49
	global_store_short v[34:35], v33, off
.LBB0_290:
	s_or_b64 exec, exec, s[40:41]
	s_waitcnt vmcnt(8)
	v_fma_f32 v28, v139, v28, v138
	v_fmac_f32_e32 v28, v140, v29
	v_fmac_f32_e32 v28, v141, v30
	v_fmac_f32_e32 v28, v143, v31
	v_fmac_f32_e32 v28, v142, v24
	v_fmac_f32_e32 v28, v48, v25
	v_pk_mul_f32 v[24:25], v[66:67], v[26:27]
	v_pk_mul_f32 v[20:21], v[68:69], v[20:21]
	v_add_f32_e32 v24, v28, v24
	v_add_f32_e32 v24, v24, v25
	v_add_f32_e32 v20, v24, v20
	v_add_f32_e32 v24, v20, v21
	v_pk_mul_f32 v[20:21], v[64:65], v[22:23]
	v_pk_mul_f32 v[16:17], v[72:73], v[16:17]
	v_add_f32_e32 v20, v24, v20
	v_add_f32_e32 v20, v20, v21
	v_add_f32_e32 v16, v20, v16
	v_add_f32_e32 v20, v16, v17
	v_pk_mul_f32 v[16:17], v[70:71], v[18:19]
	s_nop 0
	v_add_f32_e32 v16, v20, v16
	v_add_f32_e32 v16, v16, v17
	v_mul_f32_e64 v17, |v16|, s97
	v_exp_f32_e32 v18, v17
	v_min_f32_e32 v19, 0, v16
	s_nop 1
	s_nop 1
	s_nop 1
	s_nop 1
	s_nop 1
	s_nop 1
	s_nop 1
	s_nop 1
	s_nop 1
	s_nop 1
	v_add_f32_e32 v16, 1.0, v18
	v_log_f32_e32 v16, v16
	s_nop 0
	v_mul_f32_e32 v16, 0x3f317218, v16
	s_nop 1
	v_sub_f32_e32 v16, v19, v16
	v_mul_f32_e32 v16, 0x3d800000, v16
	v_cndmask_b32_e64 v16, 0, v16, s[36:37]
	v_add_f32_e32 v16, v32, v16
	s_and_saveexec_b64 s[40:41], s[36:37]
	s_cbranch_execz .LBB0_292
	v_mul_f32_e32 v21, 0x3fb8aa3b, v16
	v_exp_f32_e32 v21, v21
	v_add_u32_e32 v18, s54, v180
	v_ashrrev_i32_e32 v19, 31, v18
	s_waitcnt vmcnt(6)
	v_lshlrev_b32_e32 v20, 16, v112
	v_mul_f32_e32 v20, v21, v20
	v_lshlrev_b64 v[18:19], 9, v[18:19]
	v_cvt_pk_bf16_f32 v22, v20, v49
	v_lshl_add_u64 v[20:21], v[74:75], 0, v[18:19]
	global_store_short v[20:21], v22, off
	v_mul_f32_e32 v20, 0xbfb8aa3b, v16
	v_exp_f32_e32 v20, v20
	v_lshlrev_b32_e32 v17, 16, v111
	v_lshl_add_u64 v[18:19], v[76:77], 0, v[18:19]
	v_mul_f32_e32 v17, v20, v17
	v_cvt_pk_bf16_f32 v17, v17, v49
	global_store_short v[18:19], v17, off
.LBB0_292:
	s_or_b64 exec, exec, s[40:41]
	s_waitcnt vmcnt(2)
	v_fma_f32 v12, v139, v12, v138
	v_fmac_f32_e32 v12, v140, v13
	v_fmac_f32_e32 v12, v141, v14
	v_fmac_f32_e32 v12, v143, v15
	v_fmac_f32_e32 v12, v142, v8
	v_fmac_f32_e32 v12, v48, v9
	v_pk_mul_f32 v[8:9], v[66:67], v[10:11]
	v_pk_mul_f32 v[4:5], v[68:69], v[4:5]
	v_add_f32_e32 v8, v12, v8
	v_add_f32_e32 v8, v8, v9
	v_add_f32_e32 v4, v8, v4
	v_add_f32_e32 v8, v4, v5
	v_pk_mul_f32 v[4:5], v[64:65], v[6:7]
	v_pk_mul_f32 v[0:1], v[72:73], v[0:1]
	v_add_f32_e32 v4, v8, v4
	v_add_f32_e32 v4, v4, v5
	v_add_f32_e32 v0, v4, v0
	v_add_f32_e32 v4, v0, v1
	v_pk_mul_f32 v[0:1], v[70:71], v[2:3]
	s_nop 0
	v_add_f32_e32 v0, v4, v0
	v_add_f32_e32 v0, v0, v1
	v_mul_f32_e64 v1, |v0|, s97
	v_exp_f32_e32 v2, v1
	v_min_f32_e32 v3, 0, v0
	s_nop 1
	s_nop 1
	s_nop 1
	s_nop 1
	s_nop 1
	s_nop 1
	s_nop 1
	s_nop 1
	s_nop 1
	s_nop 1
	v_add_f32_e32 v0, 1.0, v2
	v_log_f32_e32 v0, v0
	s_nop 0
	v_mul_f32_e32 v0, 0x3f317218, v0
	s_nop 1
	v_sub_f32_e32 v0, v3, v0
	v_mul_f32_e32 v0, 0x3d800000, v0
	v_cndmask_b32_e64 v0, 0, v0, s[30:31]
	v_add_f32_e32 v111, v16, v0
	s_and_saveexec_b64 s[36:37], s[30:31]
	s_cbranch_execz .LBB0_294
	v_mul_f32_e32 v3, 0x3fb8aa3b, v111
	v_exp_f32_e32 v3, v3
	v_add_u32_e32 v0, s54, v178
	v_ashrrev_i32_e32 v1, 31, v0
	s_waitcnt vmcnt(0)
	v_lshlrev_b32_e32 v2, 16, v110
	v_mul_f32_e32 v2, v3, v2
	v_lshlrev_b64 v[0:1], 9, v[0:1]
	v_cvt_pk_bf16_f32 v5, v2, v49
	v_lshl_add_u64 v[2:3], v[74:75], 0, v[0:1]
	global_store_short v[2:3], v5, off
	v_mul_f32_e32 v2, 0xbfb8aa3b, v111
	v_exp_f32_e32 v2, v2
	v_lshlrev_b32_e32 v4, 16, v63
	v_lshl_add_u64 v[0:1], v[76:77], 0, v[0:1]
	v_mul_f32_e32 v2, v2, v4
	v_cvt_pk_bf16_f32 v2, v2, v49
	global_store_short v[0:1], v2, off
.LBB0_294:
	s_or_b64 exec, exec, s[36:37]
	global_load_dwordx4 v[114:117], v[96:97], off offset:16
	global_load_dwordx4 v[118:121], v[96:97], off
	global_load_dwordx4 v[122:125], v[96:97], off offset:48
	global_load_dwordx4 v[128:131], v[96:97], off offset:32
	v_lshlrev_b64 v[0:1], 9, v[94:95]
	v_lshl_add_u64 v[2:3], v[126:127], 0, v[0:1]
	v_lshl_add_u64 v[0:1], v[74:75], 0, v[0:1]
	global_load_ushort v110, v[2:3], off
	global_load_ushort v112, v[0:1], off
	global_load_dwordx4 v[32:35], v[102:103], off offset:48
	global_load_dwordx4 v[36:39], v[102:103], off offset:32
	global_load_dwordx4 v[40:43], v[102:103], off offset:16
	global_load_dwordx4 v[44:47], v[102:103], off
	v_lshlrev_b64 v[0:1], 9, v[98:99]
	v_lshl_add_u64 v[2:3], v[126:127], 0, v[0:1]
	v_lshl_add_u64 v[0:1], v[74:75], 0, v[0:1]
	global_load_ushort v97, v[2:3], off
	global_load_ushort v98, v[0:1], off
	global_load_dwordx4 v[16:19], v[106:107], off offset:48
	global_load_dwordx4 v[20:23], v[106:107], off offset:32
	global_load_dwordx4 v[24:27], v[106:107], off offset:16
	global_load_dwordx4 v[28:31], v[106:107], off
	v_lshlrev_b64 v[0:1], 9, v[100:101]
	v_lshl_add_u64 v[2:3], v[126:127], 0, v[0:1]
	v_lshl_add_u64 v[0:1], v[74:75], 0, v[0:1]
	global_load_ushort v95, v[2:3], off
	global_load_ushort v96, v[0:1], off
	s_nop 0
	global_load_dwordx4 v[0:3], v[108:109], off offset:48
	global_load_dwordx4 v[4:7], v[108:109], off offset:32
	global_load_dwordx4 v[8:11], v[108:109], off offset:16
	global_load_dwordx4 v[12:15], v[108:109], off
	v_lshlrev_b64 v[100:101], 9, v[104:105]
	v_lshl_add_u64 v[102:103], v[126:127], 0, v[100:101]
	v_lshl_add_u64 v[100:101], v[74:75], 0, v[100:101]
	global_load_ushort v63, v[102:103], off
	global_load_ushort v94, v[100:101], off
	s_waitcnt vmcnt(23)
	v_pk_mul_f32 v[100:101], v[66:67], v[116:117]
	s_waitcnt vmcnt(22)
	v_fma_f32 v99, v139, v118, v138
	v_fmac_f32_e32 v99, v140, v119
	v_fmac_f32_e32 v99, v141, v120
	v_fmac_f32_e32 v99, v143, v121
	v_fmac_f32_e32 v99, v142, v114
	v_fmac_f32_e32 v99, v48, v115
	v_add_f32_e32 v99, v99, v100
	v_add_f32_e32 v99, v99, v101
	s_waitcnt vmcnt(20)
	v_pk_mul_f32 v[100:101], v[68:69], v[128:129]
	s_nop 0
	v_add_f32_e32 v99, v99, v100
	v_add_f32_e32 v99, v99, v101
	v_pk_mul_f32 v[100:101], v[64:65], v[130:131]
	s_nop 0
	v_add_f32_e32 v99, v99, v100
	v_add_f32_e32 v99, v99, v101
	v_pk_mul_f32 v[100:101], v[72:73], v[122:123]
	s_nop 0
	v_add_f32_e32 v99, v99, v100
	v_add_f32_e32 v99, v99, v101
	v_pk_mul_f32 v[100:101], v[70:71], v[124:125]
	s_nop 0
	v_add_f32_e32 v99, v99, v100
	v_add_f32_e32 v99, v99, v101
	v_mul_f32_e64 v100, |v99|, s97
	v_exp_f32_e32 v102, v100
	v_min_f32_e32 v99, 0, v99
	s_nop 1
	s_nop 1
	s_nop 1
	s_nop 1
	s_nop 1
	s_nop 1
	s_nop 1
	s_nop 1
	s_nop 1
	s_nop 1
	v_add_f32_e32 v100, 1.0, v102
	v_log_f32_e32 v100, v100
	s_nop 0
	v_mul_f32_e32 v100, 0x3f317218, v100
	s_nop 1
	v_sub_f32_e32 v99, v99, v100
	v_mul_f32_e32 v99, 0x3d800000, v99
	v_cndmask_b32_e64 v99, 0, v99, s[38:39]
	v_add_f32_e32 v99, v111, v99
	s_and_saveexec_b64 s[30:31], s[38:39]
	s_cbranch_execz .LBB0_296
	v_mul_f32_e32 v103, 0x3fb8aa3b, v99
	v_exp_f32_e32 v103, v103
	v_add_u32_e32 v100, s54, v181
	v_ashrrev_i32_e32 v101, 31, v100
	s_waitcnt vmcnt(18)
	v_lshlrev_b32_e32 v102, 16, v112
	v_mul_f32_e32 v102, v103, v102
	v_lshlrev_b64 v[100:101], 9, v[100:101]
	v_cvt_pk_bf16_f32 v105, v102, v49
	v_lshl_add_u64 v[102:103], v[74:75], 0, v[100:101]
	global_store_short v[102:103], v105, off
	v_mul_f32_e32 v102, 0xbfb8aa3b, v99
	v_exp_f32_e32 v102, v102
	v_lshlrev_b32_e32 v104, 16, v110
	v_lshl_add_u64 v[100:101], v[76:77], 0, v[100:101]
	v_mul_f32_e32 v102, v102, v104
	v_cvt_pk_bf16_f32 v102, v102, v49
	global_store_short v[100:101], v102, off
.LBB0_296:
	s_or_b64 exec, exec, s[30:31]
	s_waitcnt vmcnt(14)
	v_fma_f32 v44, v139, v44, v138
	v_fmac_f32_e32 v44, v140, v45
	v_fmac_f32_e32 v44, v141, v46
	v_fmac_f32_e32 v44, v143, v47
	v_fmac_f32_e32 v44, v142, v40
	v_fmac_f32_e32 v44, v48, v41
	v_pk_mul_f32 v[40:41], v[66:67], v[42:43]
	v_pk_mul_f32 v[36:37], v[68:69], v[36:37]
	v_add_f32_e32 v40, v44, v40
	v_add_f32_e32 v40, v40, v41
	v_add_f32_e32 v36, v40, v36
	v_add_f32_e32 v40, v36, v37
	v_pk_mul_f32 v[36:37], v[64:65], v[38:39]
	v_pk_mul_f32 v[32:33], v[72:73], v[32:33]
	v_add_f32_e32 v36, v40, v36
	v_add_f32_e32 v36, v36, v37
	v_add_f32_e32 v32, v36, v32
	v_add_f32_e32 v36, v32, v33
	v_pk_mul_f32 v[32:33], v[70:71], v[34:35]
	s_nop 0
	v_add_f32_e32 v32, v36, v32
	v_add_f32_e32 v32, v32, v33
	v_mul_f32_e64 v33, |v32|, s97
	v_exp_f32_e32 v34, v33
	v_min_f32_e32 v35, 0, v32
	s_nop 1
	s_nop 1
	s_nop 1
	s_nop 1
	s_nop 1
	s_nop 1
	s_nop 1
	s_nop 1
	s_nop 1
	s_nop 1
	v_add_f32_e32 v32, 1.0, v34
	v_log_f32_e32 v32, v32
	s_nop 0
	v_mul_f32_e32 v32, 0x3f317218, v32
	s_nop 1
	v_sub_f32_e32 v32, v35, v32
	v_mul_f32_e32 v32, 0x3d800000, v32
	v_cndmask_b32_e64 v32, 0, v32, s[34:35]
	v_add_f32_e32 v32, v99, v32
	s_and_saveexec_b64 s[30:31], s[34:35]
	s_cbranch_execz .LBB0_298
	v_mul_f32_e32 v37, 0x3fb8aa3b, v32
	v_exp_f32_e32 v37, v37
	v_add_u32_e32 v34, s54, v179
	v_ashrrev_i32_e32 v35, 31, v34
	s_waitcnt vmcnt(12)
	v_lshlrev_b32_e32 v36, 16, v98
	v_mul_f32_e32 v36, v37, v36
	v_lshlrev_b64 v[34:35], 9, v[34:35]
	v_cvt_pk_bf16_f32 v38, v36, v49
	v_lshl_add_u64 v[36:37], v[74:75], 0, v[34:35]
	global_store_short v[36:37], v38, off
	v_mul_f32_e32 v36, 0xbfb8aa3b, v32
	v_exp_f32_e32 v36, v36
	v_lshlrev_b32_e32 v33, 16, v97
	v_lshl_add_u64 v[34:35], v[76:77], 0, v[34:35]
	v_mul_f32_e32 v33, v36, v33
	v_cvt_pk_bf16_f32 v33, v33, v49
	global_store_short v[34:35], v33, off
.LBB0_298:
	s_or_b64 exec, exec, s[30:31]
	s_waitcnt vmcnt(8)
	v_fma_f32 v28, v139, v28, v138
	v_fmac_f32_e32 v28, v140, v29
	v_fmac_f32_e32 v28, v141, v30
	v_fmac_f32_e32 v28, v143, v31
	v_fmac_f32_e32 v28, v142, v24
	v_fmac_f32_e32 v28, v48, v25
	v_pk_mul_f32 v[24:25], v[66:67], v[26:27]
	v_pk_mul_f32 v[20:21], v[68:69], v[20:21]
	v_add_f32_e32 v24, v28, v24
	v_add_f32_e32 v24, v24, v25
	v_add_f32_e32 v20, v24, v20
	v_add_f32_e32 v24, v20, v21
	v_pk_mul_f32 v[20:21], v[64:65], v[22:23]
	v_pk_mul_f32 v[16:17], v[72:73], v[16:17]
	v_add_f32_e32 v20, v24, v20
	v_add_f32_e32 v20, v20, v21
	v_add_f32_e32 v16, v20, v16
	v_add_f32_e32 v20, v16, v17
	v_pk_mul_f32 v[16:17], v[70:71], v[18:19]
	s_nop 0
	v_add_f32_e32 v16, v20, v16
	v_add_f32_e32 v16, v16, v17
	v_mul_f32_e64 v17, |v16|, s97
	v_exp_f32_e32 v18, v17
	v_min_f32_e32 v19, 0, v16
	s_nop 1
	s_nop 1
	s_nop 1
	s_nop 1
	s_nop 1
	s_nop 1
	s_nop 1
	s_nop 1
	s_nop 1
	s_nop 1
	v_add_f32_e32 v16, 1.0, v18
	v_log_f32_e32 v16, v16
	s_nop 0
	v_mul_f32_e32 v16, 0x3f317218, v16
	s_nop 1
	v_sub_f32_e32 v16, v19, v16
	v_mul_f32_e32 v16, 0x3d800000, v16
	v_cndmask_b32_e64 v16, 0, v16, s[26:27]
	v_add_f32_e32 v16, v32, v16
	s_and_saveexec_b64 s[30:31], s[26:27]
	s_cbranch_execz .LBB0_300
	v_mul_f32_e32 v21, 0x3fb8aa3b, v16
	v_exp_f32_e32 v21, v21
	v_add_u32_e32 v18, s54, v176
	v_ashrrev_i32_e32 v19, 31, v18
	s_waitcnt vmcnt(6)
	v_lshlrev_b32_e32 v20, 16, v96
	v_mul_f32_e32 v20, v21, v20
	v_lshlrev_b64 v[18:19], 9, v[18:19]
	v_cvt_pk_bf16_f32 v22, v20, v49
	v_lshl_add_u64 v[20:21], v[74:75], 0, v[18:19]
	global_store_short v[20:21], v22, off
	v_mul_f32_e32 v20, 0xbfb8aa3b, v16
	v_exp_f32_e32 v20, v20
	v_lshlrev_b32_e32 v17, 16, v95
	v_lshl_add_u64 v[18:19], v[76:77], 0, v[18:19]
	v_mul_f32_e32 v17, v20, v17
	v_cvt_pk_bf16_f32 v17, v17, v49
	global_store_short v[18:19], v17, off
.LBB0_300:
	s_or_b64 exec, exec, s[30:31]
	s_waitcnt vmcnt(2)
	v_fma_f32 v12, v139, v12, v138
	v_fmac_f32_e32 v12, v140, v13
	v_fmac_f32_e32 v12, v141, v14
	v_fmac_f32_e32 v12, v143, v15
	v_fmac_f32_e32 v12, v142, v8
	v_fmac_f32_e32 v12, v48, v9
	v_pk_mul_f32 v[8:9], v[66:67], v[10:11]
	v_pk_mul_f32 v[4:5], v[68:69], v[4:5]
	v_add_f32_e32 v8, v12, v8
	v_add_f32_e32 v8, v8, v9
	v_add_f32_e32 v4, v8, v4
	v_add_f32_e32 v8, v4, v5
	v_pk_mul_f32 v[4:5], v[64:65], v[6:7]
	v_pk_mul_f32 v[0:1], v[72:73], v[0:1]
	v_add_f32_e32 v4, v8, v4
	v_add_f32_e32 v4, v4, v5
	v_add_f32_e32 v0, v4, v0
	v_add_f32_e32 v4, v0, v1
	v_pk_mul_f32 v[0:1], v[70:71], v[2:3]
	s_nop 0
	v_add_f32_e32 v0, v4, v0
	v_add_f32_e32 v0, v0, v1
	v_mul_f32_e64 v1, |v0|, s97
	v_exp_f32_e32 v2, v1
	v_min_f32_e32 v3, 0, v0
	s_nop 1
	s_nop 1
	s_nop 1
	s_nop 1
	s_nop 1
	s_nop 1
	s_nop 1
	s_nop 1
	s_nop 1
	s_nop 1
	v_add_f32_e32 v0, 1.0, v2
	v_log_f32_e32 v0, v0
	s_nop 0
	v_mul_f32_e32 v0, 0x3f317218, v0
	s_nop 1
	v_sub_f32_e32 v0, v3, v0
	v_mul_f32_e32 v0, 0x3d800000, v0
	v_cndmask_b32_e64 v0, 0, v0, s[22:23]
	v_add_f32_e32 v95, v16, v0
	s_and_saveexec_b64 s[26:27], s[22:23]
	s_cbranch_execz .LBB0_302
	v_mul_f32_e32 v3, 0x3fb8aa3b, v95
	v_exp_f32_e32 v3, v3
	v_add_u32_e32 v0, s54, v146
	v_ashrrev_i32_e32 v1, 31, v0
	s_waitcnt vmcnt(0)
	v_lshlrev_b32_e32 v2, 16, v94
	v_mul_f32_e32 v2, v3, v2
	v_lshlrev_b64 v[0:1], 9, v[0:1]
	v_cvt_pk_bf16_f32 v5, v2, v49
	v_lshl_add_u64 v[2:3], v[74:75], 0, v[0:1]
	global_store_short v[2:3], v5, off
	v_mul_f32_e32 v2, 0xbfb8aa3b, v95
	v_exp_f32_e32 v2, v2
	v_lshlrev_b32_e32 v4, 16, v63
	v_lshl_add_u64 v[0:1], v[76:77], 0, v[0:1]
	v_mul_f32_e32 v2, v2, v4
	v_cvt_pk_bf16_f32 v2, v2, v49
	global_store_short v[0:1], v2, off
.LBB0_302:
	s_or_b64 exec, exec, s[26:27]
	global_load_dwordx4 v[98:101], v[80:81], off offset:16
	global_load_dwordx4 v[102:105], v[80:81], off
	global_load_dwordx4 v[106:109], v[80:81], off offset:48
	global_load_dwordx4 v[110:113], v[80:81], off offset:32
	v_lshlrev_b64 v[0:1], 9, v[78:79]
	v_lshl_add_u64 v[2:3], v[126:127], 0, v[0:1]
	v_lshl_add_u64 v[0:1], v[74:75], 0, v[0:1]
	global_load_ushort v94, v[2:3], off
	global_load_ushort v96, v[0:1], off
	global_load_dwordx4 v[32:35], v[86:87], off offset:48
	global_load_dwordx4 v[36:39], v[86:87], off offset:32
	global_load_dwordx4 v[40:43], v[86:87], off offset:16
	global_load_dwordx4 v[44:47], v[86:87], off
	v_lshlrev_b64 v[0:1], 9, v[82:83]
	v_lshl_add_u64 v[2:3], v[126:127], 0, v[0:1]
	v_lshl_add_u64 v[0:1], v[74:75], 0, v[0:1]
	global_load_ushort v81, v[2:3], off
	global_load_ushort v82, v[0:1], off
	global_load_dwordx4 v[16:19], v[90:91], off offset:48
	global_load_dwordx4 v[20:23], v[90:91], off offset:32
	global_load_dwordx4 v[24:27], v[90:91], off offset:16
	global_load_dwordx4 v[28:31], v[90:91], off
	v_lshlrev_b64 v[0:1], 9, v[84:85]
	v_lshl_add_u64 v[2:3], v[126:127], 0, v[0:1]
	v_lshl_add_u64 v[0:1], v[74:75], 0, v[0:1]
	global_load_ushort v79, v[2:3], off
	global_load_ushort v80, v[0:1], off
	s_nop 0
	global_load_dwordx4 v[0:3], v[92:93], off offset:48
	global_load_dwordx4 v[4:7], v[92:93], off offset:32
	global_load_dwordx4 v[8:11], v[92:93], off offset:16
	global_load_dwordx4 v[12:15], v[92:93], off
	v_lshlrev_b64 v[84:85], 9, v[88:89]
	v_lshl_add_u64 v[86:87], v[126:127], 0, v[84:85]
	v_lshl_add_u64 v[84:85], v[74:75], 0, v[84:85]
	global_load_ushort v63, v[86:87], off
	global_load_ushort v78, v[84:85], off
	s_waitcnt vmcnt(23)
	v_pk_mul_f32 v[84:85], v[66:67], v[100:101]
	s_waitcnt vmcnt(22)
	v_fma_f32 v83, v139, v102, v138
	v_fmac_f32_e32 v83, v140, v103
	v_fmac_f32_e32 v83, v141, v104
	v_fmac_f32_e32 v83, v143, v105
	v_fmac_f32_e32 v83, v142, v98
	v_fmac_f32_e32 v83, v48, v99
	v_add_f32_e32 v83, v83, v84
	v_add_f32_e32 v83, v83, v85
	s_waitcnt vmcnt(20)
	v_pk_mul_f32 v[84:85], v[68:69], v[110:111]
	s_nop 0
	v_add_f32_e32 v83, v83, v84
	v_add_f32_e32 v83, v83, v85
	v_pk_mul_f32 v[84:85], v[64:65], v[112:113]
	s_nop 0
	v_add_f32_e32 v83, v83, v84
	v_add_f32_e32 v83, v83, v85
	v_pk_mul_f32 v[84:85], v[72:73], v[106:107]
	s_nop 0
	v_add_f32_e32 v83, v83, v84
	v_add_f32_e32 v83, v83, v85
	v_pk_mul_f32 v[84:85], v[70:71], v[108:109]
	s_nop 0
	v_add_f32_e32 v83, v83, v84
	v_add_f32_e32 v83, v83, v85
	v_mul_f32_e64 v84, |v83|, s97
	v_exp_f32_e32 v86, v84
	v_min_f32_e32 v83, 0, v83
	s_nop 1
	s_nop 1
	s_nop 1
	s_nop 1
	s_nop 1
	s_nop 1
	s_nop 1
	s_nop 1
	s_nop 1
	s_nop 1
	v_add_f32_e32 v84, 1.0, v86
	v_log_f32_e32 v84, v84
	s_nop 0
	v_mul_f32_e32 v84, 0x3f317218, v84
	s_nop 1
	v_sub_f32_e32 v83, v83, v84
	v_mul_f32_e32 v83, 0x3d800000, v83
	v_cndmask_b32_e64 v83, 0, v83, s[28:29]
	v_add_f32_e32 v83, v95, v83
	s_and_saveexec_b64 s[22:23], s[28:29]
	s_cbranch_execz .LBB0_304
	v_mul_f32_e32 v87, 0x3fb8aa3b, v83
	v_exp_f32_e32 v87, v87
	v_add_u32_e32 v84, s54, v177
	v_ashrrev_i32_e32 v85, 31, v84
	s_waitcnt vmcnt(18)
	v_lshlrev_b32_e32 v86, 16, v96
	v_mul_f32_e32 v86, v87, v86
	v_lshlrev_b64 v[84:85], 9, v[84:85]
	v_cvt_pk_bf16_f32 v89, v86, v49
	v_lshl_add_u64 v[86:87], v[74:75], 0, v[84:85]
	global_store_short v[86:87], v89, off
	v_mul_f32_e32 v86, 0xbfb8aa3b, v83
	v_exp_f32_e32 v86, v86
	v_lshlrev_b32_e32 v88, 16, v94
	v_lshl_add_u64 v[84:85], v[76:77], 0, v[84:85]
	v_mul_f32_e32 v86, v86, v88
	v_cvt_pk_bf16_f32 v86, v86, v49
	global_store_short v[84:85], v86, off
.LBB0_304:
	s_or_b64 exec, exec, s[22:23]
	s_waitcnt vmcnt(14)
	v_fma_f32 v44, v139, v44, v138
	v_fmac_f32_e32 v44, v140, v45
	v_fmac_f32_e32 v44, v141, v46
	v_fmac_f32_e32 v44, v143, v47
	v_fmac_f32_e32 v44, v142, v40
	v_fmac_f32_e32 v44, v48, v41
	v_pk_mul_f32 v[40:41], v[66:67], v[42:43]
	v_pk_mul_f32 v[36:37], v[68:69], v[36:37]
	v_add_f32_e32 v40, v44, v40
	v_add_f32_e32 v40, v40, v41
	v_add_f32_e32 v36, v40, v36
	v_add_f32_e32 v40, v36, v37
	v_pk_mul_f32 v[36:37], v[64:65], v[38:39]
	v_pk_mul_f32 v[32:33], v[72:73], v[32:33]
	v_add_f32_e32 v36, v40, v36
	v_add_f32_e32 v36, v36, v37
	v_add_f32_e32 v32, v36, v32
	v_add_f32_e32 v36, v32, v33
	v_pk_mul_f32 v[32:33], v[70:71], v[34:35]
	s_nop 0
	v_add_f32_e32 v32, v36, v32
	v_add_f32_e32 v32, v32, v33
	v_mul_f32_e64 v33, |v32|, s97
	v_exp_f32_e32 v34, v33
	v_min_f32_e32 v35, 0, v32
	s_nop 1
	s_nop 1
	s_nop 1
	s_nop 1
	s_nop 1
	s_nop 1
	s_nop 1
	s_nop 1
	s_nop 1
	s_nop 1
	v_add_f32_e32 v32, 1.0, v34
	v_log_f32_e32 v32, v32
	s_nop 0
	v_mul_f32_e32 v32, 0x3f317218, v32
	s_nop 1
	v_sub_f32_e32 v32, v35, v32
	v_mul_f32_e32 v32, 0x3d800000, v32
	v_cndmask_b32_e64 v32, 0, v32, s[24:25]
	v_add_f32_e32 v32, v83, v32
	s_and_saveexec_b64 s[22:23], s[24:25]
	s_cbranch_execz .LBB0_306
	v_mul_f32_e32 v37, 0x3fb8aa3b, v32
	v_exp_f32_e32 v37, v37
	v_add_u32_e32 v34, s54, v147
	v_ashrrev_i32_e32 v35, 31, v34
	s_waitcnt vmcnt(12)
	v_lshlrev_b32_e32 v36, 16, v82
	v_mul_f32_e32 v36, v37, v36
	v_lshlrev_b64 v[34:35], 9, v[34:35]
	v_cvt_pk_bf16_f32 v38, v36, v49
	v_lshl_add_u64 v[36:37], v[74:75], 0, v[34:35]
	global_store_short v[36:37], v38, off
	v_mul_f32_e32 v36, 0xbfb8aa3b, v32
	v_exp_f32_e32 v36, v36
	v_lshlrev_b32_e32 v33, 16, v81
	v_lshl_add_u64 v[34:35], v[76:77], 0, v[34:35]
	v_mul_f32_e32 v33, v36, v33
	v_cvt_pk_bf16_f32 v33, v33, v49
	global_store_short v[34:35], v33, off
.LBB0_306:
	s_or_b64 exec, exec, s[22:23]
	s_waitcnt vmcnt(8)
	v_fma_f32 v28, v139, v28, v138
	v_fmac_f32_e32 v28, v140, v29
	v_fmac_f32_e32 v28, v141, v30
	v_fmac_f32_e32 v28, v143, v31
	v_fmac_f32_e32 v28, v142, v24
	v_fmac_f32_e32 v28, v48, v25
	v_pk_mul_f32 v[24:25], v[66:67], v[26:27]
	v_pk_mul_f32 v[20:21], v[68:69], v[20:21]
	v_add_f32_e32 v24, v28, v24
	v_add_f32_e32 v24, v24, v25
	v_add_f32_e32 v20, v24, v20
	v_add_f32_e32 v24, v20, v21
	v_pk_mul_f32 v[20:21], v[64:65], v[22:23]
	v_pk_mul_f32 v[16:17], v[72:73], v[16:17]
	v_add_f32_e32 v20, v24, v20
	v_add_f32_e32 v20, v20, v21
	v_add_f32_e32 v16, v20, v16
	v_add_f32_e32 v20, v16, v17
	v_pk_mul_f32 v[16:17], v[70:71], v[18:19]
	s_nop 0
	v_add_f32_e32 v16, v20, v16
	v_add_f32_e32 v16, v16, v17
	v_mul_f32_e64 v17, |v16|, s97
	v_exp_f32_e32 v18, v17
	v_min_f32_e32 v19, 0, v16
	s_nop 1
	s_nop 1
	s_nop 1
	s_nop 1
	s_nop 1
	s_nop 1
	s_nop 1
	s_nop 1
	s_nop 1
	s_nop 1
	v_add_f32_e32 v16, 1.0, v18
	v_log_f32_e32 v16, v16
	s_nop 0
	v_mul_f32_e32 v16, 0x3f317218, v16
	s_nop 1
	v_sub_f32_e32 v16, v19, v16
	v_mul_f32_e32 v16, 0x3d800000, v16
	v_cndmask_b32_e64 v16, 0, v16, s[20:21]
	v_add_f32_e32 v16, v32, v16
	s_and_saveexec_b64 s[22:23], s[20:21]
	s_cbranch_execz .LBB0_308
	v_mul_f32_e32 v21, 0x3fb8aa3b, v16
	v_exp_f32_e32 v21, v21
	v_add_u32_e32 v18, s54, v145
	v_ashrrev_i32_e32 v19, 31, v18
	s_waitcnt vmcnt(6)
	v_lshlrev_b32_e32 v20, 16, v80
	v_mul_f32_e32 v20, v21, v20
	v_lshlrev_b64 v[18:19], 9, v[18:19]
	v_cvt_pk_bf16_f32 v22, v20, v49
	v_lshl_add_u64 v[20:21], v[74:75], 0, v[18:19]
	global_store_short v[20:21], v22, off
	v_mul_f32_e32 v20, 0xbfb8aa3b, v16
	v_exp_f32_e32 v20, v20
	v_lshlrev_b32_e32 v17, 16, v79
	v_lshl_add_u64 v[18:19], v[76:77], 0, v[18:19]
	v_mul_f32_e32 v17, v20, v17
	v_cvt_pk_bf16_f32 v17, v17, v49
	global_store_short v[18:19], v17, off
.LBB0_308:
	s_or_b64 exec, exec, s[22:23]
	s_and_saveexec_b64 s[20:21], vcc
	s_cbranch_execz .LBB0_310
	s_waitcnt vmcnt(2)
	v_fmac_f32_e32 v138, v139, v12
	v_fmac_f32_e32 v138, v140, v13
	v_fmac_f32_e32 v138, v141, v14
	v_fmac_f32_e32 v138, v143, v15
	v_fmac_f32_e32 v138, v142, v8
	v_fmac_f32_e32 v138, v48, v9
	v_pk_mul_f32 v[8:9], v[66:67], v[10:11]
	v_pk_mul_f32 v[4:5], v[68:69], v[4:5]
	v_add_f32_e32 v8, v138, v8
	v_add_f32_e32 v8, v8, v9
	v_add_f32_e32 v4, v8, v4
	v_add_f32_e32 v8, v4, v5
	v_pk_mul_f32 v[4:5], v[64:65], v[6:7]
	v_pk_mul_f32 v[0:1], v[72:73], v[0:1]
	v_add_f32_e32 v4, v8, v4
	v_add_f32_e32 v4, v4, v5
	v_add_f32_e32 v0, v4, v0
	v_add_f32_e32 v4, v0, v1
	v_pk_mul_f32 v[0:1], v[70:71], v[2:3]
	s_nop 0
	v_add_f32_e32 v0, v4, v0
	v_add_f32_e32 v2, v0, v1
	v_mul_f32_e64 v0, |v2|, s97
	v_exp_f32_e32 v3, v0
	v_min_f32_e32 v2, 0, v2
	s_nop 1
	s_waitcnt vmcnt(1)
	v_lshlrev_b32_e32 v4, 16, v63
	s_nop 1
	s_nop 1
	s_nop 1
	s_nop 1
	s_nop 1
	s_nop 1
	v_add_f32_e32 v0, 1.0, v3
	v_log_f32_e32 v0, v0
	s_nop 0
	v_mul_f32_e32 v0, 0x3f317218, v0
	s_nop 1
	v_sub_f32_e32 v0, v2, v0
	v_fmac_f32_e32 v16, 0x3d800000, v0
	v_mul_f32_e32 v0, 0x3fb8aa3b, v16
	v_exp_f32_e32 v2, v0
	s_waitcnt vmcnt(0)
	v_lshlrev_b32_e32 v3, 16, v78
	v_add_u32_e32 v0, s54, v144
	v_ashrrev_i32_e32 v1, 31, v0
	v_mul_f32_e32 v2, v2, v3
	v_cvt_pk_bf16_f32 v5, v2, v49
	v_mul_f32_e32 v2, 0xbfb8aa3b, v16
	v_exp_f32_e32 v6, v2
	v_lshlrev_b64 v[0:1], 9, v[0:1]
	v_lshl_add_u64 v[2:3], v[74:75], 0, v[0:1]
	global_store_short v[2:3], v5, off
	v_mul_f32_e32 v2, v6, v4
	v_lshl_add_u64 v[0:1], v[76:77], 0, v[0:1]
	v_cvt_pk_bf16_f32 v2, v2, v49
	global_store_short v[0:1], v2, off
